# norm phases fed from registers: residual GEMM epilogue keeps x_new in accumulators and publishes per-row partial sums of squares; after the grid barrier the WG builds its h tile directly (no f32 re-re
# speedup vs baseline: 1.0171x; 1.0171x over previous
.LBB0_74:
	s_or_b64 exec, exec, s[0:1]
	v_readlane_b32 s5, v254, 57
	v_readlane_b32 s36, v253, 27
	s_add_i32 s5, s5, 1
	v_readlane_b32 s42, v253, 33
	v_readlane_b32 s43, v253, 34
	s_add_u32 s42, s42, 0xc000
	v_readlane_b32 s37, v253, 28
	v_readlane_b32 s38, v253, 29
	v_readlane_b32 s39, v253, 30
	v_readlane_b32 s40, v253, 31
	v_readlane_b32 s41, v253, 32
	v_readlane_b32 s44, v253, 35
	v_readlane_b32 s45, v253, 36
	v_readlane_b32 s46, v253, 37
	v_readlane_b32 s47, v253, 38
	v_readlane_b32 s48, v253, 39
	v_readlane_b32 s49, v253, 40
	v_readlane_b32 s50, v253, 41
	v_readlane_b32 s51, v253, 42
	s_addc_u32 s43, s43, 0
	v_writelane_b32 v253, s36, 27
	s_cmp_eq_u32 s5, 4
	s_waitcnt lgkmcnt(0)
	v_writelane_b32 v253, s37, 28
	v_writelane_b32 v253, s38, 29
	v_writelane_b32 v253, s39, 30
	v_writelane_b32 v253, s40, 31
	v_writelane_b32 v253, s41, 32
	v_writelane_b32 v253, s42, 33
	v_writelane_b32 v253, s43, 34
	v_writelane_b32 v253, s44, 35
	v_writelane_b32 v253, s45, 36
	v_writelane_b32 v253, s46, 37
	v_writelane_b32 v253, s47, 38
	v_writelane_b32 v253, s48, 39
	v_writelane_b32 v253, s49, 40
	v_writelane_b32 v253, s50, 41
	v_writelane_b32 v253, s51, 42
	s_barrier
	s_cbranch_scc1 .Lfn_skip_c
	s_lshl_b32 s0, s92, 3
	s_and_b32 s0, s0, 56
	s_bfe_u32 s1, s92, 0x30003
	s_or_b32 s0, s0, s1
	s_lshr_b32 s1, s92, 6
	v_lshrrev_b32_e32 v140, 8, v154
	v_and_b32_e32 v141, 15, v154
	v_lshl_add_u32 v140, v140, 6, v141
	v_bfe_u32 v141, v154, 6, 2
	v_bfe_u32 v142, v154, 4, 2
	v_lshlrev_b32_e32 v141, 5, v141
	v_lshl_add_u32 v141, v142, 3, v141
	v_lshlrev_b32_e32 v142, 2, v140
	v_lshlrev_b32_e32 v143, 2, v141
	v_lshlrev_b32_e32 v144, 11, v140
	v_lshl_add_u32 v144, v141, 1, v144
	s_lshl_b32 s6, s0, 12
	s_add_u32 s6, s6, s72
	s_addc_u32 s7, s73, 0
	s_add_u32 s6, s6, 0x8d00000
	s_addc_u32 s7, s7, 0
	global_load_dword v170, v142, s[6:7] offset:0
	global_load_dword v171, v142, s[6:7] offset:1024
	global_load_dword v172, v142, s[6:7] offset:2048
	global_load_dword v173, v142, s[6:7] offset:3072
	global_load_dword v174, v142, s[6:7] offset:64
	global_load_dword v175, v142, s[6:7] offset:1088
	global_load_dword v176, v142, s[6:7] offset:2112
	global_load_dword v177, v142, s[6:7] offset:3136
	global_load_dword v178, v142, s[6:7] offset:128
	global_load_dword v179, v142, s[6:7] offset:1152
	global_load_dword v180, v142, s[6:7] offset:2176
	global_load_dword v181, v142, s[6:7] offset:3200
	global_load_dword v182, v142, s[6:7] offset:192
	global_load_dword v183, v142, s[6:7] offset:1216
	global_load_dword v184, v142, s[6:7] offset:2240
	global_load_dword v185, v142, s[6:7] offset:3264
	global_load_dword v186, v142, s[6:7] offset:512
	global_load_dword v187, v142, s[6:7] offset:1536
	global_load_dword v188, v142, s[6:7] offset:2560
	global_load_dword v189, v142, s[6:7] offset:3584
	global_load_dword v190, v142, s[6:7] offset:576
	global_load_dword v191, v142, s[6:7] offset:1600
	global_load_dword v192, v142, s[6:7] offset:2624
	global_load_dword v193, v142, s[6:7] offset:3648
	global_load_dword v194, v142, s[6:7] offset:640
	global_load_dword v195, v142, s[6:7] offset:1664
	global_load_dword v196, v142, s[6:7] offset:2688
	global_load_dword v197, v142, s[6:7] offset:3712
	global_load_dword v198, v142, s[6:7] offset:704
	global_load_dword v199, v142, s[6:7] offset:1728
	global_load_dword v200, v142, s[6:7] offset:2752
	global_load_dword v201, v142, s[6:7] offset:3776
	v_readlane_b32 s4, v254, 57
	s_add_i32 s4, s4, 1
	s_lshl_b32 s4, s4, 12
	s_lshl_b32 s1, s1, 10
	v_readlane_b32 s8, v253, 19
	v_readlane_b32 s9, v253, 20
	s_add_u32 s8, s8, s4
	s_addc_u32 s9, s9, 0
	s_add_u32 s8, s8, s1
	s_addc_u32 s9, s9, 0
	s_lshr_b32 s4, s0, 3
	s_mul_i32 s4, s4, 0x9000
	s_add_u32 s4, s4, s1
	v_readlane_b32 s10, v254, 55
	v_readlane_b32 s11, v254, 56
	s_add_u32 s10, s10, s4
	s_addc_u32 s11, s11, 0
	s_add_u32 s12, s10, 0x48000
	s_addc_u32 s13, s11, 0
	s_add_u32 s10, s10, 0x49000
	s_addc_u32 s11, s11, 0
	global_load_dwordx4 v[204:207], v143, s[8:9]
	global_load_dwordx4 v[220:223], v143, s[10:11]
	global_load_dwordx4 v[236:239], v143, s[12:13]
	global_load_dwordx4 v[208:211], v143, s[8:9] offset:16
	global_load_dwordx4 v[224:227], v143, s[10:11] offset:16
	global_load_dwordx4 v[146:149], v143, s[12:13] offset:16
	global_load_dwordx4 v[212:215], v143, s[8:9] offset:512
	global_load_dwordx4 v[228:231], v143, s[10:11] offset:512
	global_load_dwordx4 v[150:153], v143, s[12:13] offset:512
	global_load_dwordx4 v[216:219], v143, s[8:9] offset:528
	global_load_dwordx4 v[232:235], v143, s[10:11] offset:528
	global_load_dwordx4 v[162:165], v143, s[12:13] offset:528
	v_readlane_b32 s14, v253, 47
	v_readlane_b32 s15, v253, 48
	s_lshl_b32 s4, s0, 19
	s_add_u32 s14, s14, s4
	s_addc_u32 s15, s15, 0
	s_lshr_b32 s4, s1, 1
	s_add_u32 s14, s14, s4
	s_addc_u32 s15, s15, 0
	s_waitcnt vmcnt(0)
	v_add_f32_e32 v170, v170, v171
	v_add_f32_e32 v172, v172, v173
	v_add_f32_e32 v174, v174, v175
	v_add_f32_e32 v176, v176, v177
	v_add_f32_e32 v178, v178, v179
	v_add_f32_e32 v180, v180, v181
	v_add_f32_e32 v182, v182, v183
	v_add_f32_e32 v184, v184, v185
	v_add_f32_e32 v186, v186, v187
	v_add_f32_e32 v188, v188, v189
	v_add_f32_e32 v190, v190, v191
	v_add_f32_e32 v192, v192, v193
	v_add_f32_e32 v194, v194, v195
	v_add_f32_e32 v196, v196, v197
	v_add_f32_e32 v198, v198, v199
	v_add_f32_e32 v200, v200, v201
	v_add_f32_e32 v170, v170, v172
	v_add_f32_e32 v174, v174, v176
	v_add_f32_e32 v178, v178, v180
	v_add_f32_e32 v182, v182, v184
	v_add_f32_e32 v186, v186, v188
	v_add_f32_e32 v190, v190, v192
	v_add_f32_e32 v194, v194, v196
	v_add_f32_e32 v198, v198, v200
	v_fmamk_f32 v170, v170, 0x3a800000, v155
	v_fmamk_f32 v174, v174, 0x3a800000, v155
	v_fmamk_f32 v178, v178, 0x3a800000, v155
	v_fmamk_f32 v182, v182, 0x3a800000, v155
	v_fmamk_f32 v186, v186, 0x3a800000, v155
	v_fmamk_f32 v190, v190, 0x3a800000, v155
	v_fmamk_f32 v194, v194, 0x3a800000, v155
	v_fmamk_f32 v198, v198, 0x3a800000, v155
	v_rsq_f32_e32 v170, v170
	v_rsq_f32_e32 v174, v174
	v_rsq_f32_e32 v178, v178
	v_rsq_f32_e32 v182, v182
	v_rsq_f32_e32 v186, v186
	v_rsq_f32_e32 v190, v190
	v_rsq_f32_e32 v194, v194
	v_rsq_f32_e32 v198, v198
	v_pk_add_f32 v[220:221], v[220:221], 1.0 op_sel_hi:[1,0]
	v_pk_add_f32 v[222:223], v[222:223], 1.0 op_sel_hi:[1,0]
	v_pk_add_f32 v[224:225], v[224:225], 1.0 op_sel_hi:[1,0]
	v_pk_add_f32 v[226:227], v[226:227], 1.0 op_sel_hi:[1,0]
	v_pk_add_f32 v[228:229], v[228:229], 1.0 op_sel_hi:[1,0]
	v_pk_add_f32 v[230:231], v[230:231], 1.0 op_sel_hi:[1,0]
	v_pk_add_f32 v[232:233], v[232:233], 1.0 op_sel_hi:[1,0]
	v_pk_add_f32 v[234:235], v[234:235], 1.0 op_sel_hi:[1,0]
	v_pk_mul_f32 v[132:133], v[132:133], v[170:171] op_sel_hi:[1,0]
	v_pk_mul_f32 v[134:135], v[134:135], v[170:171] op_sel_hi:[1,0]
	v_pk_mul_f32 v[128:129], v[128:129], v[170:171] op_sel_hi:[1,0]
	v_pk_mul_f32 v[130:131], v[130:131], v[170:171] op_sel_hi:[1,0]
	v_pk_mul_f32 v[132:133], v[204:205], v[132:133]
	v_pk_mul_f32 v[134:135], v[206:207], v[134:135]
	v_pk_mul_f32 v[128:129], v[208:209], v[128:129]
	v_pk_mul_f32 v[130:131], v[210:211], v[130:131]
	v_pk_fma_f32 v[132:133], v[220:221], v[132:133], v[236:237]
	v_pk_fma_f32 v[134:135], v[222:223], v[134:135], v[238:239]
	v_pk_fma_f32 v[128:129], v[224:225], v[128:129], v[146:147]
	v_pk_fma_f32 v[130:131], v[226:227], v[130:131], v[148:149]
	v_cvt_pk_bf16_f32 v132, v132, v133
	v_cvt_pk_bf16_f32 v133, v134, v135
	v_cvt_pk_bf16_f32 v134, v128, v129
	v_cvt_pk_bf16_f32 v135, v130, v131
	global_store_dwordx4 v144, v[132:135], s[14:15]
	v_pk_mul_f32 v[60:61], v[60:61], v[170:171] op_sel_hi:[1,0]
	v_pk_mul_f32 v[62:63], v[62:63], v[170:171] op_sel_hi:[1,0]
	v_pk_mul_f32 v[56:57], v[56:57], v[170:171] op_sel_hi:[1,0]
	v_pk_mul_f32 v[58:59], v[58:59], v[170:171] op_sel_hi:[1,0]
	v_pk_mul_f32 v[60:61], v[212:213], v[60:61]
	v_pk_mul_f32 v[62:63], v[214:215], v[62:63]
	v_pk_mul_f32 v[56:57], v[216:217], v[56:57]
	v_pk_mul_f32 v[58:59], v[218:219], v[58:59]
	v_pk_fma_f32 v[60:61], v[228:229], v[60:61], v[150:151]
	v_pk_fma_f32 v[62:63], v[230:231], v[62:63], v[152:153]
	v_pk_fma_f32 v[56:57], v[232:233], v[56:57], v[162:163]
	v_pk_fma_f32 v[58:59], v[234:235], v[58:59], v[164:165]
	v_cvt_pk_bf16_f32 v60, v60, v61
	v_cvt_pk_bf16_f32 v61, v62, v63
	v_cvt_pk_bf16_f32 v62, v56, v57
	v_cvt_pk_bf16_f32 v63, v58, v59
	global_store_dwordx4 v144, v[60:63], s[14:15] offset:256
	s_add_u32 s14, s14, 0x8000
	s_addc_u32 s15, s15, 0
	v_pk_mul_f32 v[124:125], v[124:125], v[174:175] op_sel_hi:[1,0]
	v_pk_mul_f32 v[126:127], v[126:127], v[174:175] op_sel_hi:[1,0]
	v_pk_mul_f32 v[120:121], v[120:121], v[174:175] op_sel_hi:[1,0]
	v_pk_mul_f32 v[122:123], v[122:123], v[174:175] op_sel_hi:[1,0]
	v_pk_mul_f32 v[124:125], v[204:205], v[124:125]
	v_pk_mul_f32 v[126:127], v[206:207], v[126:127]
	v_pk_mul_f32 v[120:121], v[208:209], v[120:121]
	v_pk_mul_f32 v[122:123], v[210:211], v[122:123]
	v_pk_fma_f32 v[124:125], v[220:221], v[124:125], v[236:237]
	v_pk_fma_f32 v[126:127], v[222:223], v[126:127], v[238:239]
	v_pk_fma_f32 v[120:121], v[224:225], v[120:121], v[146:147]
	v_pk_fma_f32 v[122:123], v[226:227], v[122:123], v[148:149]
	v_cvt_pk_bf16_f32 v124, v124, v125
	v_cvt_pk_bf16_f32 v125, v126, v127
	v_cvt_pk_bf16_f32 v126, v120, v121
	v_cvt_pk_bf16_f32 v127, v122, v123
	global_store_dwordx4 v144, v[124:127], s[14:15]
	v_pk_mul_f32 v[52:53], v[52:53], v[174:175] op_sel_hi:[1,0]
	v_pk_mul_f32 v[54:55], v[54:55], v[174:175] op_sel_hi:[1,0]
	v_pk_mul_f32 v[48:49], v[48:49], v[174:175] op_sel_hi:[1,0]
	v_pk_mul_f32 v[50:51], v[50:51], v[174:175] op_sel_hi:[1,0]
	v_pk_mul_f32 v[52:53], v[212:213], v[52:53]
	v_pk_mul_f32 v[54:55], v[214:215], v[54:55]
	v_pk_mul_f32 v[48:49], v[216:217], v[48:49]
	v_pk_mul_f32 v[50:51], v[218:219], v[50:51]
	v_pk_fma_f32 v[52:53], v[228:229], v[52:53], v[150:151]
	v_pk_fma_f32 v[54:55], v[230:231], v[54:55], v[152:153]
	v_pk_fma_f32 v[48:49], v[232:233], v[48:49], v[162:163]
	v_pk_fma_f32 v[50:51], v[234:235], v[50:51], v[164:165]
	v_cvt_pk_bf16_f32 v52, v52, v53
	v_cvt_pk_bf16_f32 v53, v54, v55
	v_cvt_pk_bf16_f32 v54, v48, v49
	v_cvt_pk_bf16_f32 v55, v50, v51
	global_store_dwordx4 v144, v[52:55], s[14:15] offset:256
	s_add_u32 s14, s14, 0x8000
	s_addc_u32 s15, s15, 0
	v_pk_mul_f32 v[116:117], v[116:117], v[178:179] op_sel_hi:[1,0]
	v_pk_mul_f32 v[118:119], v[118:119], v[178:179] op_sel_hi:[1,0]
	v_pk_mul_f32 v[112:113], v[112:113], v[178:179] op_sel_hi:[1,0]
	v_pk_mul_f32 v[114:115], v[114:115], v[178:179] op_sel_hi:[1,0]
	v_pk_mul_f32 v[116:117], v[204:205], v[116:117]
	v_pk_mul_f32 v[118:119], v[206:207], v[118:119]
	v_pk_mul_f32 v[112:113], v[208:209], v[112:113]
	v_pk_mul_f32 v[114:115], v[210:211], v[114:115]
	v_pk_fma_f32 v[116:117], v[220:221], v[116:117], v[236:237]
	v_pk_fma_f32 v[118:119], v[222:223], v[118:119], v[238:239]
	v_pk_fma_f32 v[112:113], v[224:225], v[112:113], v[146:147]
	v_pk_fma_f32 v[114:115], v[226:227], v[114:115], v[148:149]
	v_cvt_pk_bf16_f32 v116, v116, v117
	v_cvt_pk_bf16_f32 v117, v118, v119
	v_cvt_pk_bf16_f32 v118, v112, v113
	v_cvt_pk_bf16_f32 v119, v114, v115
	global_store_dwordx4 v144, v[116:119], s[14:15]
	v_pk_mul_f32 v[44:45], v[44:45], v[178:179] op_sel_hi:[1,0]
	v_pk_mul_f32 v[46:47], v[46:47], v[178:179] op_sel_hi:[1,0]
	v_pk_mul_f32 v[40:41], v[40:41], v[178:179] op_sel_hi:[1,0]
	v_pk_mul_f32 v[42:43], v[42:43], v[178:179] op_sel_hi:[1,0]
	v_pk_mul_f32 v[44:45], v[212:213], v[44:45]
	v_pk_mul_f32 v[46:47], v[214:215], v[46:47]
	v_pk_mul_f32 v[40:41], v[216:217], v[40:41]
	v_pk_mul_f32 v[42:43], v[218:219], v[42:43]
	v_pk_fma_f32 v[44:45], v[228:229], v[44:45], v[150:151]
	v_pk_fma_f32 v[46:47], v[230:231], v[46:47], v[152:153]
	v_pk_fma_f32 v[40:41], v[232:233], v[40:41], v[162:163]
	v_pk_fma_f32 v[42:43], v[234:235], v[42:43], v[164:165]
	v_cvt_pk_bf16_f32 v44, v44, v45
	v_cvt_pk_bf16_f32 v45, v46, v47
	v_cvt_pk_bf16_f32 v46, v40, v41
	v_cvt_pk_bf16_f32 v47, v42, v43
	global_store_dwordx4 v144, v[44:47], s[14:15] offset:256
	s_add_u32 s14, s14, 0x8000
	s_addc_u32 s15, s15, 0
	v_pk_mul_f32 v[108:109], v[108:109], v[182:183] op_sel_hi:[1,0]
	v_pk_mul_f32 v[110:111], v[110:111], v[182:183] op_sel_hi:[1,0]
	v_pk_mul_f32 v[104:105], v[104:105], v[182:183] op_sel_hi:[1,0]
	v_pk_mul_f32 v[106:107], v[106:107], v[182:183] op_sel_hi:[1,0]
	v_pk_mul_f32 v[108:109], v[204:205], v[108:109]
	v_pk_mul_f32 v[110:111], v[206:207], v[110:111]
	v_pk_mul_f32 v[104:105], v[208:209], v[104:105]
	v_pk_mul_f32 v[106:107], v[210:211], v[106:107]
	v_pk_fma_f32 v[108:109], v[220:221], v[108:109], v[236:237]
	v_pk_fma_f32 v[110:111], v[222:223], v[110:111], v[238:239]
	v_pk_fma_f32 v[104:105], v[224:225], v[104:105], v[146:147]
	v_pk_fma_f32 v[106:107], v[226:227], v[106:107], v[148:149]
	v_cvt_pk_bf16_f32 v108, v108, v109
	v_cvt_pk_bf16_f32 v109, v110, v111
	v_cvt_pk_bf16_f32 v110, v104, v105
	v_cvt_pk_bf16_f32 v111, v106, v107
	global_store_dwordx4 v144, v[108:111], s[14:15]
	v_pk_mul_f32 v[36:37], v[36:37], v[182:183] op_sel_hi:[1,0]
	v_pk_mul_f32 v[38:39], v[38:39], v[182:183] op_sel_hi:[1,0]
	v_pk_mul_f32 v[32:33], v[32:33], v[182:183] op_sel_hi:[1,0]
	v_pk_mul_f32 v[34:35], v[34:35], v[182:183] op_sel_hi:[1,0]
	v_pk_mul_f32 v[36:37], v[212:213], v[36:37]
	v_pk_mul_f32 v[38:39], v[214:215], v[38:39]
	v_pk_mul_f32 v[32:33], v[216:217], v[32:33]
	v_pk_mul_f32 v[34:35], v[218:219], v[34:35]
	v_pk_fma_f32 v[36:37], v[228:229], v[36:37], v[150:151]
	v_pk_fma_f32 v[38:39], v[230:231], v[38:39], v[152:153]
	v_pk_fma_f32 v[32:33], v[232:233], v[32:33], v[162:163]
	v_pk_fma_f32 v[34:35], v[234:235], v[34:35], v[164:165]
	v_cvt_pk_bf16_f32 v36, v36, v37
	v_cvt_pk_bf16_f32 v37, v38, v39
	v_cvt_pk_bf16_f32 v38, v32, v33
	v_cvt_pk_bf16_f32 v39, v34, v35
	global_store_dwordx4 v144, v[36:39], s[14:15] offset:256
	s_add_u32 s14, s14, 0x28000
	s_addc_u32 s15, s15, 0
	v_pk_mul_f32 v[100:101], v[100:101], v[186:187] op_sel_hi:[1,0]
	v_pk_mul_f32 v[102:103], v[102:103], v[186:187] op_sel_hi:[1,0]
	v_pk_mul_f32 v[96:97], v[96:97], v[186:187] op_sel_hi:[1,0]
	v_pk_mul_f32 v[98:99], v[98:99], v[186:187] op_sel_hi:[1,0]
	v_pk_mul_f32 v[100:101], v[204:205], v[100:101]
	v_pk_mul_f32 v[102:103], v[206:207], v[102:103]
	v_pk_mul_f32 v[96:97], v[208:209], v[96:97]
	v_pk_mul_f32 v[98:99], v[210:211], v[98:99]
	v_pk_fma_f32 v[100:101], v[220:221], v[100:101], v[236:237]
	v_pk_fma_f32 v[102:103], v[222:223], v[102:103], v[238:239]
	v_pk_fma_f32 v[96:97], v[224:225], v[96:97], v[146:147]
	v_pk_fma_f32 v[98:99], v[226:227], v[98:99], v[148:149]
	v_cvt_pk_bf16_f32 v100, v100, v101
	v_cvt_pk_bf16_f32 v101, v102, v103
	v_cvt_pk_bf16_f32 v102, v96, v97
	v_cvt_pk_bf16_f32 v103, v98, v99
	global_store_dwordx4 v144, v[100:103], s[14:15]
	v_pk_mul_f32 v[28:29], v[28:29], v[186:187] op_sel_hi:[1,0]
	v_pk_mul_f32 v[30:31], v[30:31], v[186:187] op_sel_hi:[1,0]
	v_pk_mul_f32 v[24:25], v[24:25], v[186:187] op_sel_hi:[1,0]
	v_pk_mul_f32 v[26:27], v[26:27], v[186:187] op_sel_hi:[1,0]
	v_pk_mul_f32 v[28:29], v[212:213], v[28:29]
	v_pk_mul_f32 v[30:31], v[214:215], v[30:31]
	v_pk_mul_f32 v[24:25], v[216:217], v[24:25]
	v_pk_mul_f32 v[26:27], v[218:219], v[26:27]
	v_pk_fma_f32 v[28:29], v[228:229], v[28:29], v[150:151]
	v_pk_fma_f32 v[30:31], v[230:231], v[30:31], v[152:153]
	v_pk_fma_f32 v[24:25], v[232:233], v[24:25], v[162:163]
	v_pk_fma_f32 v[26:27], v[234:235], v[26:27], v[164:165]
	v_cvt_pk_bf16_f32 v28, v28, v29
	v_cvt_pk_bf16_f32 v29, v30, v31
	v_cvt_pk_bf16_f32 v30, v24, v25
	v_cvt_pk_bf16_f32 v31, v26, v27
	global_store_dwordx4 v144, v[28:31], s[14:15] offset:256
	s_add_u32 s14, s14, 0x8000
	s_addc_u32 s15, s15, 0
	v_pk_mul_f32 v[92:93], v[92:93], v[190:191] op_sel_hi:[1,0]
	v_pk_mul_f32 v[94:95], v[94:95], v[190:191] op_sel_hi:[1,0]
	v_pk_mul_f32 v[88:89], v[88:89], v[190:191] op_sel_hi:[1,0]
	v_pk_mul_f32 v[90:91], v[90:91], v[190:191] op_sel_hi:[1,0]
	v_pk_mul_f32 v[92:93], v[204:205], v[92:93]
	v_pk_mul_f32 v[94:95], v[206:207], v[94:95]
	v_pk_mul_f32 v[88:89], v[208:209], v[88:89]
	v_pk_mul_f32 v[90:91], v[210:211], v[90:91]
	v_pk_fma_f32 v[92:93], v[220:221], v[92:93], v[236:237]
	v_pk_fma_f32 v[94:95], v[222:223], v[94:95], v[238:239]
	v_pk_fma_f32 v[88:89], v[224:225], v[88:89], v[146:147]
	v_pk_fma_f32 v[90:91], v[226:227], v[90:91], v[148:149]
	v_cvt_pk_bf16_f32 v92, v92, v93
	v_cvt_pk_bf16_f32 v93, v94, v95
	v_cvt_pk_bf16_f32 v94, v88, v89
	v_cvt_pk_bf16_f32 v95, v90, v91
	global_store_dwordx4 v144, v[92:95], s[14:15]
	v_pk_mul_f32 v[20:21], v[20:21], v[190:191] op_sel_hi:[1,0]
	v_pk_mul_f32 v[22:23], v[22:23], v[190:191] op_sel_hi:[1,0]
	v_pk_mul_f32 v[16:17], v[16:17], v[190:191] op_sel_hi:[1,0]
	v_pk_mul_f32 v[18:19], v[18:19], v[190:191] op_sel_hi:[1,0]
	v_pk_mul_f32 v[20:21], v[212:213], v[20:21]
	v_pk_mul_f32 v[22:23], v[214:215], v[22:23]
	v_pk_mul_f32 v[16:17], v[216:217], v[16:17]
	v_pk_mul_f32 v[18:19], v[218:219], v[18:19]
	v_pk_fma_f32 v[20:21], v[228:229], v[20:21], v[150:151]
	v_pk_fma_f32 v[22:23], v[230:231], v[22:23], v[152:153]
	v_pk_fma_f32 v[16:17], v[232:233], v[16:17], v[162:163]
	v_pk_fma_f32 v[18:19], v[234:235], v[18:19], v[164:165]
	v_cvt_pk_bf16_f32 v20, v20, v21
	v_cvt_pk_bf16_f32 v21, v22, v23
	v_cvt_pk_bf16_f32 v22, v16, v17
	v_cvt_pk_bf16_f32 v23, v18, v19
	global_store_dwordx4 v144, v[20:23], s[14:15] offset:256
	s_add_u32 s14, s14, 0x8000
	s_addc_u32 s15, s15, 0
	v_pk_mul_f32 v[76:77], v[76:77], v[194:195] op_sel_hi:[1,0]
	v_pk_mul_f32 v[78:79], v[78:79], v[194:195] op_sel_hi:[1,0]
	v_pk_mul_f32 v[72:73], v[72:73], v[194:195] op_sel_hi:[1,0]
	v_pk_mul_f32 v[74:75], v[74:75], v[194:195] op_sel_hi:[1,0]
	v_pk_mul_f32 v[76:77], v[204:205], v[76:77]
	v_pk_mul_f32 v[78:79], v[206:207], v[78:79]
	v_pk_mul_f32 v[72:73], v[208:209], v[72:73]
	v_pk_mul_f32 v[74:75], v[210:211], v[74:75]
	v_pk_fma_f32 v[76:77], v[220:221], v[76:77], v[236:237]
	v_pk_fma_f32 v[78:79], v[222:223], v[78:79], v[238:239]
	v_pk_fma_f32 v[72:73], v[224:225], v[72:73], v[146:147]
	v_pk_fma_f32 v[74:75], v[226:227], v[74:75], v[148:149]
	v_cvt_pk_bf16_f32 v76, v76, v77
	v_cvt_pk_bf16_f32 v77, v78, v79
	v_cvt_pk_bf16_f32 v78, v72, v73
	v_cvt_pk_bf16_f32 v79, v74, v75
	global_store_dwordx4 v144, v[76:79], s[14:15]
	v_pk_mul_f32 v[12:13], v[12:13], v[194:195] op_sel_hi:[1,0]
	v_pk_mul_f32 v[14:15], v[14:15], v[194:195] op_sel_hi:[1,0]
	v_pk_mul_f32 v[8:9], v[8:9], v[194:195] op_sel_hi:[1,0]
	v_pk_mul_f32 v[10:11], v[10:11], v[194:195] op_sel_hi:[1,0]
	v_pk_mul_f32 v[12:13], v[212:213], v[12:13]
	v_pk_mul_f32 v[14:15], v[214:215], v[14:15]
	v_pk_mul_f32 v[8:9], v[216:217], v[8:9]
	v_pk_mul_f32 v[10:11], v[218:219], v[10:11]
	v_pk_fma_f32 v[12:13], v[228:229], v[12:13], v[150:151]
	v_pk_fma_f32 v[14:15], v[230:231], v[14:15], v[152:153]
	v_pk_fma_f32 v[8:9], v[232:233], v[8:9], v[162:163]
	v_pk_fma_f32 v[10:11], v[234:235], v[10:11], v[164:165]
	v_cvt_pk_bf16_f32 v12, v12, v13
	v_cvt_pk_bf16_f32 v13, v14, v15
	v_cvt_pk_bf16_f32 v14, v8, v9
	v_cvt_pk_bf16_f32 v15, v10, v11
	global_store_dwordx4 v144, v[12:15], s[14:15] offset:256
	s_add_u32 s14, s14, 0x8000
	s_addc_u32 s15, s15, 0
	v_pk_mul_f32 v[68:69], v[68:69], v[198:199] op_sel_hi:[1,0]
	v_pk_mul_f32 v[70:71], v[70:71], v[198:199] op_sel_hi:[1,0]
	v_pk_mul_f32 v[64:65], v[64:65], v[198:199] op_sel_hi:[1,0]
	v_pk_mul_f32 v[66:67], v[66:67], v[198:199] op_sel_hi:[1,0]
	v_pk_mul_f32 v[68:69], v[204:205], v[68:69]
	v_pk_mul_f32 v[70:71], v[206:207], v[70:71]
	v_pk_mul_f32 v[64:65], v[208:209], v[64:65]
	v_pk_mul_f32 v[66:67], v[210:211], v[66:67]
	v_pk_fma_f32 v[68:69], v[220:221], v[68:69], v[236:237]
	v_pk_fma_f32 v[70:71], v[222:223], v[70:71], v[238:239]
	v_pk_fma_f32 v[64:65], v[224:225], v[64:65], v[146:147]
	v_pk_fma_f32 v[66:67], v[226:227], v[66:67], v[148:149]
	v_cvt_pk_bf16_f32 v68, v68, v69
	v_cvt_pk_bf16_f32 v69, v70, v71
	v_cvt_pk_bf16_f32 v70, v64, v65
	v_cvt_pk_bf16_f32 v71, v66, v67
	global_store_dwordx4 v144, v[68:71], s[14:15]
	v_pk_mul_f32 v[246:247], v[246:247], v[198:199] op_sel_hi:[1,0]
	v_pk_mul_f32 v[248:249], v[248:249], v[198:199] op_sel_hi:[1,0]
	v_pk_mul_f32 v[242:243], v[242:243], v[198:199] op_sel_hi:[1,0]
	v_pk_mul_f32 v[244:245], v[244:245], v[198:199] op_sel_hi:[1,0]
	v_pk_mul_f32 v[246:247], v[212:213], v[246:247]
	v_pk_mul_f32 v[248:249], v[214:215], v[248:249]
	v_pk_mul_f32 v[242:243], v[216:217], v[242:243]
	v_pk_mul_f32 v[244:245], v[218:219], v[244:245]
	v_pk_fma_f32 v[246:247], v[228:229], v[246:247], v[150:151]
	v_pk_fma_f32 v[248:249], v[230:231], v[248:249], v[152:153]
	v_pk_fma_f32 v[242:243], v[232:233], v[242:243], v[162:163]
	v_pk_fma_f32 v[244:245], v[234:235], v[244:245], v[164:165]
	v_cvt_pk_bf16_f32 v246, v246, v247
	v_cvt_pk_bf16_f32 v247, v248, v249
	v_cvt_pk_bf16_f32 v248, v242, v243
	v_cvt_pk_bf16_f32 v249, v244, v245
	global_store_dwordx4 v144, v[246:249], s[14:15] offset:256
.Lfn_skip_c:
	v_readlane_b32 s5, v254, 57
	s_add_i32 s5, s5, 1
	s_cmp_eq_u32 s5, 4
	s_cbranch_scc0 .LBB0_75
	s_getpc_b64 s[98:99]

.LBB0_75:
	s_mul_i32 s0, s5, 0x12000
	s_mov_b32 s1, s52
	s_lshl_b64 s[0:1], s[0:1], 2
	v_readlane_b32 s4, v253, 45
	s_add_u32 s6, s4, s0
	v_readlane_b32 s0, v253, 46
	s_addc_u32 s7, s0, s1
	v_readlane_b32 s36, v253, 11
	v_writelane_b32 v254, s6, 55
	v_readlane_b32 s37, v253, 12
	s_cmp_eq_u32 s5, 0
	v_writelane_b32 v254, s7, 56
	s_mov_b64 s[0:1], s[36:37]
	s_cselect_b32 s1, s1, s71
	s_cselect_b32 s0, s0, s70
	v_writelane_b32 v254, s5, 57
	s_lshl_b32 s4, s5, 10
	s_mov_b32 s5, s52
	v_writelane_b32 v254, s4, 58
	v_mov_b32_e32 v0, v154
	v_mov_b32_e32 v2, v154
	v_writelane_b32 v254, s5, 59
	v_readlane_b32 s4, v253, 0
	v_readfirstlane_b32 s5, v2
	s_ashr_i32 s5, s5, 6
	s_lshl_b32 s4, s4, 3
	s_and_b32 s5, s5, -4
	v_lshrrev_b32_e32 v1, 6, v0
	s_add_i32 s5, s5, s4
	v_and_or_b32 v16, v1, 3, s5
	s_movk_i32 s4, 0x4000
	v_cmp_gt_i32_e32 vcc, s4, v16
	v_readlane_b32 s38, v253, 13
	v_readlane_b32 s39, v253, 14
	v_readlane_b32 s40, v253, 15
	v_readlane_b32 s41, v253, 16
	v_readlane_b32 s42, v253, 17
	v_readlane_b32 s43, v253, 18
	v_readlane_b32 s44, v253, 19
	v_readlane_b32 s45, v253, 20
	v_readlane_b32 s46, v253, 21
	v_readlane_b32 s47, v253, 22
	v_readlane_b32 s48, v253, 23
	v_readlane_b32 s49, v253, 24
	v_readlane_b32 s50, v253, 25
	v_readlane_b32 s51, v253, 26
	s_and_saveexec_b64 s[4:5], vcc
	v_readlane_b32 s10, v254, 47
	v_readlane_b32 s12, v254, 49
	s_movk_i32 s8, 0x3fff
	v_readlane_b32 s11, v254, 48
	v_readlane_b32 s13, v254, 50
	v_readlane_b32 s9, v254, 57
	s_cmp_lg_u32 s9, 0
	s_cbranch_scc1 .LBB0_78
	s_cbranch_execz .LBB0_78
	v_readlane_b32 s6, v254, 58
	v_readlane_b32 s7, v254, 59
	v_readlane_b32 s36, v253, 11
	s_lshl_b64 s[6:7], s[6:7], 2
	v_readlane_b32 s44, v253, 19
	v_readlane_b32 s45, v253, 20
	s_add_u32 s6, s44, s6
	v_and_b32_e32 v2, 63, v0
	s_addc_u32 s7, s45, s7
	v_lshlrev_b32_e32 v136, 5, v2
	v_lshl_add_u64 v[18:19], s[6:7], 0, v[136:137]
	v_readlane_b32 s6, v254, 55
	v_readlane_b32 s7, v254, 56
	v_lshlrev_b32_e32 v0, 2, v2
	v_ashrrev_i32_e32 v17, 31, v16
	v_lshl_add_u64 v[20:21], s[6:7], 0, v[136:137]
	s_mov_b64 s[6:7], 0x1000
	v_xor_b32_e32 v29, 64, v0
	v_xor_b32_e32 v34, 0x80, v0
	v_lshl_add_u64 v[22:23], v[20:21], 0, s[6:7]
	v_lshlrev_b64 v[0:1], 11, v[16:17]
	v_readlane_b32 s6, v253, 47
	v_lshl_or_b32 v0, v2, 4, v0
	v_readlane_b32 s7, v253, 48
	v_readlane_b32 s37, v253, 12
	v_readlane_b32 s38, v253, 13
	v_lshl_add_u64 v[24:25], s[6:7], 0, v[0:1]
	v_lshlrev_b64 v[0:1], 12, v[16:17]
	v_or_b32_e32 v0, v0, v136
	v_lshl_add_u64 v[26:27], s[0:1], 0, v[0:1]
	s_mov_b64 s[6:7], 0
	v_readlane_b32 s39, v253, 14
	v_readlane_b32 s40, v253, 15
	v_readlane_b32 s41, v253, 16
	v_readlane_b32 s42, v253, 17
	v_readlane_b32 s43, v253, 18
	v_readlane_b32 s46, v253, 21
	v_readlane_b32 s47, v253, 22
	v_readlane_b32 s48, v253, 23
	v_readlane_b32 s49, v253, 24
	v_readlane_b32 s50, v253, 25
	v_readlane_b32 s51, v253, 26

.LBB0_149:
	s_or_b64 exec, exec, s[4:5]
	v_mov_b32_e32 v72, v154
	s_lshr_b32 s5, s12, 3
	v_and_b32_e32 v136, 15, v72
	v_lshrrev_b32_e32 v73, 1, v72
	v_ashrrev_i32_e32 v72, 2, v72
	s_lshl_b32 s4, s14, 8
	s_mul_i32 s5, s5, 0x9000
	v_and_b32_e32 v152, 0xffffffc0, v72
	s_add_u32 s12, s9, s5
	v_ashrrev_i32_e32 v153, 31, v152
	s_mov_b32 s5, s52
	v_and_b32_e32 v73, 0x78, v73
	v_lshl_add_u64 v[140:141], v[152:153], 0, s[4:5]
	v_lshl_or_b32 v146, s13, 8, v73
	v_or_b32_e32 v140, v140, v136
	v_ashrrev_i32_e32 v147, 31, v146
	v_lshlrev_b64 v[144:145], 10, v[140:141]
	s_addc_u32 s13, s10, 0
	v_lshl_add_u64 v[140:141], v[144:145], 0, v[146:147]
	v_lshl_add_u64 v[148:149], v[146:147], 2, s[12:13]
	v_lshlrev_b64 v[140:141], 2, v[140:141]
	s_nop 1
	v_readfirstlane_b32 s38, v140
	v_readfirstlane_b32 s39, v141
	s_nop 1
	v_subrev_u32_e32 v139, s38, v140
	s_add_u32 s40, s0, s38
	s_addc_u32 s41, s1, s39
	s_add_u32 s42, s70, s38
	s_addc_u32 s43, s71, s39
	s_mov_b64 s[44:45], s[40:41]
	s_mov_b64 s[46:47], s[42:43]
	global_load_dwordx4 v[234:237], v[148:149], off
	global_load_dwordx4 v[238:241], v[148:149], off offset:16
	global_load_dwordx4 v[242:245], v[148:149], off offset:512
	global_load_dwordx4 v[246:249], v[148:149], off offset:528
	global_load_dwordx4 v[178:181], v139, s[40:41]
	global_load_dwordx4 v[182:185], v139, s[40:41] offset:16
	s_add_u32 s40, s40, 0x10000
	s_addc_u32 s41, s41, 0
	global_load_dwordx4 v[186:189], v139, s[40:41]
	global_load_dwordx4 v[190:193], v139, s[40:41] offset:16
	s_add_u32 s40, s40, 0x10000
	s_addc_u32 s41, s41, 0
	global_load_dwordx4 v[194:197], v139, s[40:41]
	global_load_dwordx4 v[198:201], v139, s[40:41] offset:16
	s_add_u32 s40, s40, 0x10000
	s_addc_u32 s41, s41, 0
	global_load_dwordx4 v[202:205], v139, s[40:41]
	global_load_dwordx4 v[206:209], v139, s[40:41] offset:16
	s_add_u32 s40, s40, 0x50000
	s_addc_u32 s41, s41, 0
	global_load_dwordx4 v[210:213], v139, s[40:41]
	global_load_dwordx4 v[214:217], v139, s[40:41] offset:16
	s_add_u32 s40, s40, 0x10000
	s_addc_u32 s41, s41, 0
	global_load_dwordx4 v[218:221], v139, s[40:41]
	global_load_dwordx4 v[222:225], v139, s[40:41] offset:16
	s_add_u32 s40, s40, 0x10000
	s_addc_u32 s41, s41, 0
	global_load_dwordx4 v[226:229], v139, s[40:41]
	global_load_dwordx4 v[230:233], v139, s[40:41] offset:16
	s_add_u32 s40, s40, 0x10000
	s_addc_u32 s41, s41, 0
	s_waitcnt vmcnt(12)
	v_pk_mul_f32 v[132:133], v[132:133], v[234:235]
	v_pk_mul_f32 v[134:135], v[134:135], v[236:237]
	v_pk_mul_f32 v[128:129], v[128:129], v[238:239]
	v_pk_mul_f32 v[130:131], v[130:131], v[240:241]
	v_pk_fma_f32 v[132:133], v[132:133], 0.5, v[178:179] op_sel_hi:[1,0,1]
	v_pk_fma_f32 v[134:135], v[134:135], 0.5, v[180:181] op_sel_hi:[1,0,1]
	v_pk_fma_f32 v[128:129], v[128:129], 0.5, v[182:183] op_sel_hi:[1,0,1]
	v_pk_fma_f32 v[130:131], v[130:131], 0.5, v[184:185] op_sel_hi:[1,0,1]
	global_store_dwordx4 v139, v[132:135], s[42:43]
	global_store_dwordx4 v139, v[128:131], s[42:43] offset:16
	s_add_u32 s42, s42, 0x10000
	s_addc_u32 s43, s43, 0
	global_load_dwordx4 v[178:181], v139, s[40:41]
	global_load_dwordx4 v[182:185], v139, s[40:41] offset:16
	s_mov_b64 s[40:41], s[44:45]
	s_waitcnt vmcnt(14)
	v_pk_mul_f32 v[124:125], v[124:125], v[234:235]
	v_pk_mul_f32 v[126:127], v[126:127], v[236:237]
	v_pk_mul_f32 v[120:121], v[120:121], v[238:239]
	v_pk_mul_f32 v[122:123], v[122:123], v[240:241]
	v_pk_fma_f32 v[124:125], v[124:125], 0.5, v[186:187] op_sel_hi:[1,0,1]
	v_pk_fma_f32 v[126:127], v[126:127], 0.5, v[188:189] op_sel_hi:[1,0,1]
	v_pk_fma_f32 v[120:121], v[120:121], 0.5, v[190:191] op_sel_hi:[1,0,1]
	v_pk_fma_f32 v[122:123], v[122:123], 0.5, v[192:193] op_sel_hi:[1,0,1]
	global_store_dwordx4 v139, v[124:127], s[42:43]
	global_store_dwordx4 v139, v[120:123], s[42:43] offset:16
	s_add_u32 s42, s42, 0x10000
	s_addc_u32 s43, s43, 0
	global_load_dwordx4 v[186:189], v139, s[40:41] offset:512
	global_load_dwordx4 v[190:193], v139, s[40:41] offset:528
	s_add_u32 s40, s40, 0x10000
	s_addc_u32 s41, s41, 0
	s_waitcnt vmcnt(16)
	v_pk_mul_f32 v[116:117], v[116:117], v[234:235]
	v_pk_mul_f32 v[118:119], v[118:119], v[236:237]
	v_pk_mul_f32 v[112:113], v[112:113], v[238:239]
	v_pk_mul_f32 v[114:115], v[114:115], v[240:241]
	v_pk_fma_f32 v[116:117], v[116:117], 0.5, v[194:195] op_sel_hi:[1,0,1]
	v_pk_fma_f32 v[118:119], v[118:119], 0.5, v[196:197] op_sel_hi:[1,0,1]
	v_pk_fma_f32 v[112:113], v[112:113], 0.5, v[198:199] op_sel_hi:[1,0,1]
	v_pk_fma_f32 v[114:115], v[114:115], 0.5, v[200:201] op_sel_hi:[1,0,1]
	global_store_dwordx4 v139, v[116:119], s[42:43]
	global_store_dwordx4 v139, v[112:115], s[42:43] offset:16
	s_add_u32 s42, s42, 0x10000
	s_addc_u32 s43, s43, 0
	global_load_dwordx4 v[194:197], v139, s[40:41] offset:512
	global_load_dwordx4 v[198:201], v139, s[40:41] offset:528
	s_add_u32 s40, s40, 0x10000
	s_addc_u32 s41, s41, 0
	s_waitcnt vmcnt(18)
	v_pk_mul_f32 v[108:109], v[108:109], v[234:235]
	v_pk_mul_f32 v[110:111], v[110:111], v[236:237]
	v_pk_mul_f32 v[104:105], v[104:105], v[238:239]
	v_pk_mul_f32 v[106:107], v[106:107], v[240:241]
	v_pk_fma_f32 v[108:109], v[108:109], 0.5, v[202:203] op_sel_hi:[1,0,1]
	v_pk_fma_f32 v[110:111], v[110:111], 0.5, v[204:205] op_sel_hi:[1,0,1]
	v_pk_fma_f32 v[104:105], v[104:105], 0.5, v[206:207] op_sel_hi:[1,0,1]
	v_pk_fma_f32 v[106:107], v[106:107], 0.5, v[208:209] op_sel_hi:[1,0,1]
	global_store_dwordx4 v139, v[108:111], s[42:43]
	global_store_dwordx4 v139, v[104:107], s[42:43] offset:16
	s_add_u32 s42, s42, 0x50000
	s_addc_u32 s43, s43, 0
	global_load_dwordx4 v[202:205], v139, s[40:41] offset:512
	global_load_dwordx4 v[206:209], v139, s[40:41] offset:528
	s_add_u32 s40, s40, 0x10000
	s_addc_u32 s41, s41, 0
	s_waitcnt vmcnt(20)
	v_pk_mul_f32 v[100:101], v[100:101], v[234:235]
	v_pk_mul_f32 v[102:103], v[102:103], v[236:237]
	v_pk_mul_f32 v[96:97], v[96:97], v[238:239]
	v_pk_mul_f32 v[98:99], v[98:99], v[240:241]
	v_pk_fma_f32 v[100:101], v[100:101], 0.5, v[210:211] op_sel_hi:[1,0,1]
	v_pk_fma_f32 v[102:103], v[102:103], 0.5, v[212:213] op_sel_hi:[1,0,1]
	v_pk_fma_f32 v[96:97], v[96:97], 0.5, v[214:215] op_sel_hi:[1,0,1]
	v_pk_fma_f32 v[98:99], v[98:99], 0.5, v[216:217] op_sel_hi:[1,0,1]
	global_store_dwordx4 v139, v[100:103], s[42:43]
	global_store_dwordx4 v139, v[96:99], s[42:43] offset:16
	s_add_u32 s42, s42, 0x10000
	s_addc_u32 s43, s43, 0
	global_load_dwordx4 v[210:213], v139, s[40:41] offset:512
	global_load_dwordx4 v[214:217], v139, s[40:41] offset:528
	s_add_u32 s40, s40, 0x50000
	s_addc_u32 s41, s41, 0
	s_waitcnt vmcnt(22)
	v_pk_mul_f32 v[92:93], v[92:93], v[234:235]
	v_pk_mul_f32 v[94:95], v[94:95], v[236:237]
	v_pk_mul_f32 v[88:89], v[88:89], v[238:239]
	v_pk_mul_f32 v[90:91], v[90:91], v[240:241]
	v_pk_fma_f32 v[92:93], v[92:93], 0.5, v[218:219] op_sel_hi:[1,0,1]
	v_pk_fma_f32 v[94:95], v[94:95], 0.5, v[220:221] op_sel_hi:[1,0,1]
	v_pk_fma_f32 v[88:89], v[88:89], 0.5, v[222:223] op_sel_hi:[1,0,1]
	v_pk_fma_f32 v[90:91], v[90:91], 0.5, v[224:225] op_sel_hi:[1,0,1]
	global_store_dwordx4 v139, v[92:95], s[42:43]
	global_store_dwordx4 v139, v[88:91], s[42:43] offset:16
	s_add_u32 s42, s42, 0x10000
	s_addc_u32 s43, s43, 0
	global_load_dwordx4 v[218:221], v139, s[40:41] offset:512
	global_load_dwordx4 v[222:225], v139, s[40:41] offset:528
	s_add_u32 s40, s40, 0x10000
	s_addc_u32 s41, s41, 0
	s_waitcnt vmcnt(24)
	v_pk_mul_f32 v[84:85], v[84:85], v[234:235]
	v_pk_mul_f32 v[86:87], v[86:87], v[236:237]
	v_pk_mul_f32 v[80:81], v[80:81], v[238:239]
	v_pk_mul_f32 v[82:83], v[82:83], v[240:241]
	v_pk_fma_f32 v[84:85], v[84:85], 0.5, v[226:227] op_sel_hi:[1,0,1]
	v_pk_fma_f32 v[86:87], v[86:87], 0.5, v[228:229] op_sel_hi:[1,0,1]
	v_pk_fma_f32 v[80:81], v[80:81], 0.5, v[230:231] op_sel_hi:[1,0,1]
	v_pk_fma_f32 v[82:83], v[82:83], 0.5, v[232:233] op_sel_hi:[1,0,1]
	global_store_dwordx4 v139, v[84:87], s[42:43]
	global_store_dwordx4 v139, v[80:83], s[42:43] offset:16
	s_add_u32 s42, s42, 0x10000
	s_addc_u32 s43, s43, 0
	global_load_dwordx4 v[226:229], v139, s[40:41] offset:512
	global_load_dwordx4 v[230:233], v139, s[40:41] offset:528
	s_add_u32 s40, s40, 0x10000
	s_addc_u32 s41, s41, 0
	s_waitcnt vmcnt(24)
	v_pk_mul_f32 v[68:69], v[68:69], v[234:235]
	v_pk_mul_f32 v[70:71], v[70:71], v[236:237]
	v_pk_mul_f32 v[64:65], v[64:65], v[238:239]
	v_pk_mul_f32 v[66:67], v[66:67], v[240:241]
	v_pk_fma_f32 v[68:69], v[68:69], 0.5, v[178:179] op_sel_hi:[1,0,1]
	v_pk_fma_f32 v[70:71], v[70:71], 0.5, v[180:181] op_sel_hi:[1,0,1]
	v_pk_fma_f32 v[64:65], v[64:65], 0.5, v[182:183] op_sel_hi:[1,0,1]
	v_pk_fma_f32 v[66:67], v[66:67], 0.5, v[184:185] op_sel_hi:[1,0,1]
	global_store_dwordx4 v139, v[68:71], s[42:43]
	global_store_dwordx4 v139, v[64:67], s[42:43] offset:16
	s_mov_b64 s[42:43], s[46:47]
	global_load_dwordx4 v[178:181], v139, s[40:41] offset:512
	global_load_dwordx4 v[182:185], v139, s[40:41] offset:528
	s_add_u32 s40, s40, 0x10000
	s_addc_u32 s41, s41, 0
	s_waitcnt vmcnt(24)
	v_pk_mul_f32 v[60:61], v[60:61], v[242:243]
	v_pk_mul_f32 v[62:63], v[62:63], v[244:245]
	v_pk_mul_f32 v[56:57], v[56:57], v[246:247]
	v_pk_mul_f32 v[58:59], v[58:59], v[248:249]
	v_pk_fma_f32 v[60:61], v[60:61], 0.5, v[186:187] op_sel_hi:[1,0,1]
	v_pk_fma_f32 v[62:63], v[62:63], 0.5, v[188:189] op_sel_hi:[1,0,1]
	v_pk_fma_f32 v[56:57], v[56:57], 0.5, v[190:191] op_sel_hi:[1,0,1]
	v_pk_fma_f32 v[58:59], v[58:59], 0.5, v[192:193] op_sel_hi:[1,0,1]
	global_store_dwordx4 v139, v[60:63], s[42:43] offset:512
	global_store_dwordx4 v139, v[56:59], s[42:43] offset:528
	s_add_u32 s42, s42, 0x10000
	s_addc_u32 s43, s43, 0
	global_load_dwordx4 v[186:189], v139, s[40:41] offset:512
	global_load_dwordx4 v[190:193], v139, s[40:41] offset:528
	s_waitcnt vmcnt(24)
	v_pk_mul_f32 v[52:53], v[52:53], v[242:243]
	v_pk_mul_f32 v[54:55], v[54:55], v[244:245]
	v_pk_mul_f32 v[48:49], v[48:49], v[246:247]
	v_pk_mul_f32 v[50:51], v[50:51], v[248:249]
	v_pk_fma_f32 v[52:53], v[52:53], 0.5, v[194:195] op_sel_hi:[1,0,1]
	v_pk_fma_f32 v[54:55], v[54:55], 0.5, v[196:197] op_sel_hi:[1,0,1]
	v_pk_fma_f32 v[48:49], v[48:49], 0.5, v[198:199] op_sel_hi:[1,0,1]
	v_pk_fma_f32 v[50:51], v[50:51], 0.5, v[200:201] op_sel_hi:[1,0,1]
	global_store_dwordx4 v139, v[52:55], s[42:43] offset:512
	global_store_dwordx4 v139, v[48:51], s[42:43] offset:528
	s_add_u32 s42, s42, 0x10000
	s_addc_u32 s43, s43, 0
	s_waitcnt vmcnt(22)
	v_pk_mul_f32 v[44:45], v[44:45], v[242:243]
	v_pk_mul_f32 v[46:47], v[46:47], v[244:245]
	v_pk_mul_f32 v[40:41], v[40:41], v[246:247]
	v_pk_mul_f32 v[42:43], v[42:43], v[248:249]
	v_pk_fma_f32 v[44:45], v[44:45], 0.5, v[202:203] op_sel_hi:[1,0,1]
	v_pk_fma_f32 v[46:47], v[46:47], 0.5, v[204:205] op_sel_hi:[1,0,1]
	v_pk_fma_f32 v[40:41], v[40:41], 0.5, v[206:207] op_sel_hi:[1,0,1]
	v_pk_fma_f32 v[42:43], v[42:43], 0.5, v[208:209] op_sel_hi:[1,0,1]
	global_store_dwordx4 v139, v[44:47], s[42:43] offset:512
	global_store_dwordx4 v139, v[40:43], s[42:43] offset:528
	s_add_u32 s42, s42, 0x10000
	s_addc_u32 s43, s43, 0
	s_waitcnt vmcnt(20)
	v_pk_mul_f32 v[32:33], v[32:33], v[242:243]
	v_pk_mul_f32 v[34:35], v[34:35], v[244:245]
	v_pk_mul_f32 v[24:25], v[24:25], v[246:247]
	v_pk_mul_f32 v[26:27], v[26:27], v[248:249]
	v_pk_fma_f32 v[32:33], v[32:33], 0.5, v[210:211] op_sel_hi:[1,0,1]
	v_pk_fma_f32 v[34:35], v[34:35], 0.5, v[212:213] op_sel_hi:[1,0,1]
	v_pk_fma_f32 v[24:25], v[24:25], 0.5, v[214:215] op_sel_hi:[1,0,1]
	v_pk_fma_f32 v[26:27], v[26:27], 0.5, v[216:217] op_sel_hi:[1,0,1]
	global_store_dwordx4 v139, v[32:35], s[42:43] offset:512
	global_store_dwordx4 v139, v[24:27], s[42:43] offset:528
	s_add_u32 s42, s42, 0x50000
	s_addc_u32 s43, s43, 0
	s_waitcnt vmcnt(18)
	v_pk_mul_f32 v[36:37], v[36:37], v[242:243]
	v_pk_mul_f32 v[38:39], v[38:39], v[244:245]
	v_pk_mul_f32 v[28:29], v[28:29], v[246:247]
	v_pk_mul_f32 v[30:31], v[30:31], v[248:249]
	v_pk_fma_f32 v[36:37], v[36:37], 0.5, v[218:219] op_sel_hi:[1,0,1]
	v_pk_fma_f32 v[38:39], v[38:39], 0.5, v[220:221] op_sel_hi:[1,0,1]
	v_pk_fma_f32 v[28:29], v[28:29], 0.5, v[222:223] op_sel_hi:[1,0,1]
	v_pk_fma_f32 v[30:31], v[30:31], 0.5, v[224:225] op_sel_hi:[1,0,1]
	global_store_dwordx4 v139, v[36:39], s[42:43] offset:512
	global_store_dwordx4 v139, v[28:31], s[42:43] offset:528
	s_add_u32 s42, s42, 0x10000
	s_addc_u32 s43, s43, 0
	s_waitcnt vmcnt(16)
	v_pk_mul_f32 v[20:21], v[20:21], v[242:243]
	v_pk_mul_f32 v[22:23], v[22:23], v[244:245]
	v_pk_mul_f32 v[16:17], v[16:17], v[246:247]
	v_pk_mul_f32 v[18:19], v[18:19], v[248:249]
	v_pk_fma_f32 v[20:21], v[20:21], 0.5, v[226:227] op_sel_hi:[1,0,1]
	v_pk_fma_f32 v[22:23], v[22:23], 0.5, v[228:229] op_sel_hi:[1,0,1]
	v_pk_fma_f32 v[16:17], v[16:17], 0.5, v[230:231] op_sel_hi:[1,0,1]
	v_pk_fma_f32 v[18:19], v[18:19], 0.5, v[232:233] op_sel_hi:[1,0,1]
	global_store_dwordx4 v139, v[20:23], s[42:43] offset:512
	global_store_dwordx4 v139, v[16:19], s[42:43] offset:528
	s_add_u32 s42, s42, 0x10000
	s_addc_u32 s43, s43, 0
	s_waitcnt vmcnt(14)
	v_pk_mul_f32 v[12:13], v[12:13], v[242:243]
	v_pk_mul_f32 v[14:15], v[14:15], v[244:245]
	v_pk_mul_f32 v[8:9], v[8:9], v[246:247]
	v_pk_mul_f32 v[10:11], v[10:11], v[248:249]
	v_pk_fma_f32 v[12:13], v[12:13], 0.5, v[178:179] op_sel_hi:[1,0,1]
	v_pk_fma_f32 v[14:15], v[14:15], 0.5, v[180:181] op_sel_hi:[1,0,1]
	v_pk_fma_f32 v[8:9], v[8:9], 0.5, v[182:183] op_sel_hi:[1,0,1]
	v_pk_fma_f32 v[10:11], v[10:11], 0.5, v[184:185] op_sel_hi:[1,0,1]
	global_store_dwordx4 v139, v[12:15], s[42:43] offset:512
	global_store_dwordx4 v139, v[8:11], s[42:43] offset:528
	s_add_u32 s42, s42, 0x10000
	s_addc_u32 s43, s43, 0
	s_waitcnt vmcnt(12)
	v_pk_mul_f32 v[4:5], v[4:5], v[242:243]
	v_pk_mul_f32 v[6:7], v[6:7], v[244:245]
	v_pk_mul_f32 v[0:1], v[0:1], v[246:247]
	v_pk_mul_f32 v[2:3], v[2:3], v[248:249]
	v_pk_fma_f32 v[4:5], v[4:5], 0.5, v[186:187] op_sel_hi:[1,0,1]
	v_pk_fma_f32 v[6:7], v[6:7], 0.5, v[188:189] op_sel_hi:[1,0,1]
	v_pk_fma_f32 v[0:1], v[0:1], 0.5, v[190:191] op_sel_hi:[1,0,1]
	v_pk_fma_f32 v[2:3], v[2:3], 0.5, v[192:193] op_sel_hi:[1,0,1]
	global_store_dwordx4 v139, v[4:7], s[42:43] offset:512
	global_store_dwordx4 v139, v[0:3], s[42:43] offset:528
	v_pk_mul_f32 v[200:201], v[132:133], v[132:133]
	v_pk_mul_f32 v[202:203], v[124:125], v[124:125]
	v_pk_mul_f32 v[204:205], v[116:117], v[116:117]
	v_pk_mul_f32 v[206:207], v[108:109], v[108:109]
	v_pk_mul_f32 v[208:209], v[100:101], v[100:101]
	v_pk_mul_f32 v[210:211], v[92:93], v[92:93]
	v_pk_mul_f32 v[212:213], v[84:85], v[84:85]
	v_pk_mul_f32 v[214:215], v[68:69], v[68:69]
	v_pk_fma_f32 v[200:201], v[134:135], v[134:135], v[200:201]
	v_pk_fma_f32 v[202:203], v[126:127], v[126:127], v[202:203]
	v_pk_fma_f32 v[204:205], v[118:119], v[118:119], v[204:205]
	v_pk_fma_f32 v[206:207], v[110:111], v[110:111], v[206:207]
	v_pk_fma_f32 v[208:209], v[102:103], v[102:103], v[208:209]
	v_pk_fma_f32 v[210:211], v[94:95], v[94:95], v[210:211]
	v_pk_fma_f32 v[212:213], v[86:87], v[86:87], v[212:213]
	v_pk_fma_f32 v[214:215], v[70:71], v[70:71], v[214:215]
	v_pk_fma_f32 v[200:201], v[128:129], v[128:129], v[200:201]
	v_pk_fma_f32 v[202:203], v[120:121], v[120:121], v[202:203]
	v_pk_fma_f32 v[204:205], v[112:113], v[112:113], v[204:205]
	v_pk_fma_f32 v[206:207], v[104:105], v[104:105], v[206:207]
	v_pk_fma_f32 v[208:209], v[96:97], v[96:97], v[208:209]
	v_pk_fma_f32 v[210:211], v[88:89], v[88:89], v[210:211]
	v_pk_fma_f32 v[212:213], v[80:81], v[80:81], v[212:213]
	v_pk_fma_f32 v[214:215], v[64:65], v[64:65], v[214:215]
	v_pk_fma_f32 v[200:201], v[130:131], v[130:131], v[200:201]
	v_pk_fma_f32 v[202:203], v[122:123], v[122:123], v[202:203]
	v_pk_fma_f32 v[204:205], v[114:115], v[114:115], v[204:205]
	v_pk_fma_f32 v[206:207], v[106:107], v[106:107], v[206:207]
	v_pk_fma_f32 v[208:209], v[98:99], v[98:99], v[208:209]
	v_pk_fma_f32 v[210:211], v[90:91], v[90:91], v[210:211]
	v_pk_fma_f32 v[212:213], v[82:83], v[82:83], v[212:213]
	v_pk_fma_f32 v[214:215], v[66:67], v[66:67], v[214:215]
	v_pk_fma_f32 v[200:201], v[60:61], v[60:61], v[200:201]
	v_pk_fma_f32 v[202:203], v[52:53], v[52:53], v[202:203]
	v_pk_fma_f32 v[204:205], v[44:45], v[44:45], v[204:205]
	v_pk_fma_f32 v[206:207], v[32:33], v[32:33], v[206:207]
	v_pk_fma_f32 v[208:209], v[36:37], v[36:37], v[208:209]
	v_pk_fma_f32 v[210:211], v[20:21], v[20:21], v[210:211]
	v_pk_fma_f32 v[212:213], v[12:13], v[12:13], v[212:213]
	v_pk_fma_f32 v[214:215], v[4:5], v[4:5], v[214:215]
	v_pk_fma_f32 v[200:201], v[62:63], v[62:63], v[200:201]
	v_pk_fma_f32 v[202:203], v[54:55], v[54:55], v[202:203]
	v_pk_fma_f32 v[204:205], v[46:47], v[46:47], v[204:205]
	v_pk_fma_f32 v[206:207], v[34:35], v[34:35], v[206:207]
	v_pk_fma_f32 v[208:209], v[38:39], v[38:39], v[208:209]
	v_pk_fma_f32 v[210:211], v[22:23], v[22:23], v[210:211]
	v_pk_fma_f32 v[212:213], v[14:15], v[14:15], v[212:213]
	v_pk_fma_f32 v[214:215], v[6:7], v[6:7], v[214:215]
	v_pk_fma_f32 v[200:201], v[56:57], v[56:57], v[200:201]
	v_pk_fma_f32 v[202:203], v[48:49], v[48:49], v[202:203]
	v_pk_fma_f32 v[204:205], v[40:41], v[40:41], v[204:205]
	v_pk_fma_f32 v[206:207], v[24:25], v[24:25], v[206:207]
	v_pk_fma_f32 v[208:209], v[28:29], v[28:29], v[208:209]
	v_pk_fma_f32 v[210:211], v[16:17], v[16:17], v[210:211]
	v_pk_fma_f32 v[212:213], v[8:9], v[8:9], v[212:213]
	v_pk_fma_f32 v[214:215], v[0:1], v[0:1], v[214:215]
	v_pk_fma_f32 v[200:201], v[58:59], v[58:59], v[200:201]
	v_pk_fma_f32 v[202:203], v[50:51], v[50:51], v[202:203]
	v_pk_fma_f32 v[204:205], v[42:43], v[42:43], v[204:205]
	v_pk_fma_f32 v[206:207], v[26:27], v[26:27], v[206:207]
	v_pk_fma_f32 v[208:209], v[30:31], v[30:31], v[208:209]
	v_pk_fma_f32 v[210:211], v[18:19], v[18:19], v[210:211]
	v_pk_fma_f32 v[212:213], v[10:11], v[10:11], v[212:213]
	v_pk_fma_f32 v[214:215], v[2:3], v[2:3], v[214:215]
	v_add_f32_e32 v216, v200, v201
	v_add_f32_e32 v217, v202, v203
	v_add_f32_e32 v218, v204, v205
	v_add_f32_e32 v219, v206, v207
	v_add_f32_e32 v220, v208, v209
	v_add_f32_e32 v221, v210, v211
	v_add_f32_e32 v222, v212, v213
	v_add_f32_e32 v223, v214, v215
	v_and_b32_e32 v224, 63, v154
	v_xor_b32_e32 v225, 32, v224
	v_xor_b32_e32 v224, 16, v224
	v_lshlrev_b32_e32 v224, 2, v224
	v_lshlrev_b32_e32 v225, 2, v225
	ds_bpermute_b32 v226, v224, v216
	ds_bpermute_b32 v227, v224, v217
	ds_bpermute_b32 v228, v224, v218
	ds_bpermute_b32 v229, v224, v219
	ds_bpermute_b32 v230, v224, v220
	ds_bpermute_b32 v231, v224, v221
	ds_bpermute_b32 v232, v224, v222
	ds_bpermute_b32 v233, v224, v223
	s_waitcnt lgkmcnt(0)
	v_add_f32_e32 v216, v216, v226
	v_add_f32_e32 v217, v217, v227
	v_add_f32_e32 v218, v218, v228
	v_add_f32_e32 v219, v219, v229
	v_add_f32_e32 v220, v220, v230
	v_add_f32_e32 v221, v221, v231
	v_add_f32_e32 v222, v222, v232
	v_add_f32_e32 v223, v223, v233
	ds_bpermute_b32 v226, v225, v216
	ds_bpermute_b32 v227, v225, v217
	ds_bpermute_b32 v228, v225, v218
	ds_bpermute_b32 v229, v225, v219
	ds_bpermute_b32 v230, v225, v220
	ds_bpermute_b32 v231, v225, v221
	ds_bpermute_b32 v232, v225, v222
	ds_bpermute_b32 v233, v225, v223
	s_waitcnt lgkmcnt(0)
	v_add_f32_e32 v216, v216, v226
	v_add_f32_e32 v217, v217, v227
	v_add_f32_e32 v218, v218, v228
	v_add_f32_e32 v219, v219, v229
	v_add_f32_e32 v220, v220, v230
	v_add_f32_e32 v221, v221, v231
	v_add_f32_e32 v222, v222, v232
	v_add_f32_e32 v223, v223, v233
	v_bfe_u32 v234, v154, 6, 2
	v_lshlrev_b32_e32 v234, 8, v234
	v_lshrrev_b32_e32 v235, 8, v154
	v_lshl_add_u32 v234, v235, 6, v234
	v_and_b32_e32 v235, 15, v154
	v_add_u32_e32 v234, v234, v235
	v_lshlrev_b32_e32 v234, 2, v234
	ds_write_b32 v234, v216 offset:0
	ds_write_b32 v234, v217 offset:64
	ds_write_b32 v234, v218 offset:128
	ds_write_b32 v234, v219 offset:192
	ds_write_b32 v234, v220 offset:512
	ds_write_b32 v234, v221 offset:576
	ds_write_b32 v234, v222 offset:640
	ds_write_b32 v234, v223 offset:704
	s_waitcnt lgkmcnt(0)
	s_barrier
	v_cmp_gt_u32_e32 vcc, 0x100, v154
	s_and_saveexec_b64 s[48:49], vcc
	v_lshlrev_b32_e32 v235, 2, v154
	ds_read_b32 v236, v235
	ds_read_b32 v237, v235 offset:1024
	ds_read_b32 v238, v235 offset:2048
	ds_read_b32 v239, v235 offset:3072
	s_lshl_b32 s50, s6, 3
	s_and_b32 s50, s50, 56
	s_bfe_u32 s51, s6, 0x30003
	s_or_b32 s50, s50, s51
	s_lshl_b32 s50, s50, 2
	s_lshr_b32 s51, s6, 6
	s_or_b32 s50, s50, s51
	s_lshl_b32 s50, s50, 10
	s_add_u32 s50, s50, s72
	s_addc_u32 s51, s73, 0
	s_add_u32 s50, s50, 0x8d00000
	s_addc_u32 s51, s51, 0
	s_waitcnt lgkmcnt(0)
	v_add_f32_e32 v236, v236, v237
	v_add_f32_e32 v238, v238, v239
	v_add_f32_e32 v236, v236, v238
	global_store_dword v235, v236, s[50:51]
	s_mov_b64 exec, s[48:49]
	s_mov_b32 s92, s6
	v_mov_b64_e32 v[242:243], v[0:1]
	v_mov_b64_e32 v[244:245], v[2:3]
	v_mov_b64_e32 v[246:247], v[4:5]
	v_mov_b64_e32 v[248:249], v[6:7]
	s_add_i32 s6, s6, s74
	s_add_i32 s11, s11, s20
	s_cmpk_lt_i32 s6, 0x100
	s_cbranch_scc0 .LBB0_156

.LBB0_186:
	s_or_b64 exec, exec, s[0:1]
	v_mov_b32_e32 v0, v154
	v_mov_b32_e32 v2, v154
	s_waitcnt lgkmcnt(0)
	s_barrier
	s_lshl_b32 s0, s92, 3
	s_and_b32 s0, s0, 56
	s_bfe_u32 s1, s92, 0x30003
	s_or_b32 s0, s0, s1
	s_lshr_b32 s1, s92, 6
	v_lshrrev_b32_e32 v140, 8, v154
	v_and_b32_e32 v141, 15, v154
	v_lshl_add_u32 v140, v140, 6, v141
	v_bfe_u32 v141, v154, 6, 2
	v_bfe_u32 v142, v154, 4, 2
	v_lshlrev_b32_e32 v141, 5, v141
	v_lshl_add_u32 v141, v142, 3, v141
	v_lshlrev_b32_e32 v142, 2, v140
	v_lshlrev_b32_e32 v143, 2, v141
	v_lshlrev_b32_e32 v144, 11, v140
	v_lshl_add_u32 v144, v141, 1, v144
	s_lshl_b32 s6, s0, 12
	s_add_u32 s6, s6, s72
	s_addc_u32 s7, s73, 0
	s_add_u32 s6, s6, 0x8d00000
	s_addc_u32 s7, s7, 0
	global_load_dword v170, v142, s[6:7] offset:0
	global_load_dword v171, v142, s[6:7] offset:1024
	global_load_dword v172, v142, s[6:7] offset:2048
	global_load_dword v173, v142, s[6:7] offset:3072
	global_load_dword v174, v142, s[6:7] offset:64
	global_load_dword v175, v142, s[6:7] offset:1088
	global_load_dword v176, v142, s[6:7] offset:2112
	global_load_dword v177, v142, s[6:7] offset:3136
	global_load_dword v178, v142, s[6:7] offset:128
	global_load_dword v179, v142, s[6:7] offset:1152
	global_load_dword v180, v142, s[6:7] offset:2176
	global_load_dword v181, v142, s[6:7] offset:3200
	global_load_dword v182, v142, s[6:7] offset:192
	global_load_dword v183, v142, s[6:7] offset:1216
	global_load_dword v184, v142, s[6:7] offset:2240
	global_load_dword v185, v142, s[6:7] offset:3264
	global_load_dword v186, v142, s[6:7] offset:512
	global_load_dword v187, v142, s[6:7] offset:1536
	global_load_dword v188, v142, s[6:7] offset:2560
	global_load_dword v189, v142, s[6:7] offset:3584
	global_load_dword v190, v142, s[6:7] offset:576
	global_load_dword v191, v142, s[6:7] offset:1600
	global_load_dword v192, v142, s[6:7] offset:2624
	global_load_dword v193, v142, s[6:7] offset:3648
	global_load_dword v194, v142, s[6:7] offset:640
	global_load_dword v195, v142, s[6:7] offset:1664
	global_load_dword v196, v142, s[6:7] offset:2688
	global_load_dword v197, v142, s[6:7] offset:3712
	global_load_dword v198, v142, s[6:7] offset:704
	global_load_dword v199, v142, s[6:7] offset:1728
	global_load_dword v200, v142, s[6:7] offset:2752
	global_load_dword v201, v142, s[6:7] offset:3776
	v_readlane_b32 s4, v254, 57
	s_lshl_b32 s4, s4, 12
	s_lshl_b32 s1, s1, 10
	v_readlane_b32 s8, v253, 25
	v_readlane_b32 s9, v253, 26
	s_add_u32 s8, s8, s4
	s_addc_u32 s9, s9, 0
	s_add_u32 s8, s8, s1
	s_addc_u32 s9, s9, 0
	s_lshr_b32 s4, s0, 3
	s_mul_i32 s4, s4, 0x9000
	s_add_u32 s4, s4, s1
	v_readlane_b32 s10, v254, 55
	v_readlane_b32 s11, v254, 56
	s_add_u32 s10, s10, s4
	s_addc_u32 s11, s11, 0
	s_add_u32 s12, s10, 0x3000
	s_addc_u32 s13, s11, 0
	s_add_u32 s10, s10, 0x4000
	s_addc_u32 s11, s11, 0
	global_load_dwordx4 v[204:207], v143, s[8:9]
	global_load_dwordx4 v[220:223], v143, s[10:11]
	global_load_dwordx4 v[236:239], v143, s[12:13]
	global_load_dwordx4 v[208:211], v143, s[8:9] offset:16
	global_load_dwordx4 v[224:227], v143, s[10:11] offset:16
	global_load_dwordx4 v[146:149], v143, s[12:13] offset:16
	global_load_dwordx4 v[212:215], v143, s[8:9] offset:512
	global_load_dwordx4 v[228:231], v143, s[10:11] offset:512
	global_load_dwordx4 v[150:153], v143, s[12:13] offset:512
	global_load_dwordx4 v[216:219], v143, s[8:9] offset:528
	global_load_dwordx4 v[232:235], v143, s[10:11] offset:528
	global_load_dwordx4 v[162:165], v143, s[12:13] offset:528
	v_readlane_b32 s14, v253, 47
	v_readlane_b32 s15, v253, 48
	s_lshl_b32 s4, s0, 19
	s_add_u32 s14, s14, s4
	s_addc_u32 s15, s15, 0
	s_lshr_b32 s4, s1, 1
	s_add_u32 s14, s14, s4
	s_addc_u32 s15, s15, 0
	s_waitcnt vmcnt(0)
	v_add_f32_e32 v170, v170, v171
	v_add_f32_e32 v172, v172, v173
	v_add_f32_e32 v174, v174, v175
	v_add_f32_e32 v176, v176, v177
	v_add_f32_e32 v178, v178, v179
	v_add_f32_e32 v180, v180, v181
	v_add_f32_e32 v182, v182, v183
	v_add_f32_e32 v184, v184, v185
	v_add_f32_e32 v186, v186, v187
	v_add_f32_e32 v188, v188, v189
	v_add_f32_e32 v190, v190, v191
	v_add_f32_e32 v192, v192, v193
	v_add_f32_e32 v194, v194, v195
	v_add_f32_e32 v196, v196, v197
	v_add_f32_e32 v198, v198, v199
	v_add_f32_e32 v200, v200, v201
	v_add_f32_e32 v170, v170, v172
	v_add_f32_e32 v174, v174, v176
	v_add_f32_e32 v178, v178, v180
	v_add_f32_e32 v182, v182, v184
	v_add_f32_e32 v186, v186, v188
	v_add_f32_e32 v190, v190, v192
	v_add_f32_e32 v194, v194, v196
	v_add_f32_e32 v198, v198, v200
	v_fmamk_f32 v170, v170, 0x3a800000, v155
	v_fmamk_f32 v174, v174, 0x3a800000, v155
	v_fmamk_f32 v178, v178, 0x3a800000, v155
	v_fmamk_f32 v182, v182, 0x3a800000, v155
	v_fmamk_f32 v186, v186, 0x3a800000, v155
	v_fmamk_f32 v190, v190, 0x3a800000, v155
	v_fmamk_f32 v194, v194, 0x3a800000, v155
	v_fmamk_f32 v198, v198, 0x3a800000, v155
	v_rsq_f32_e32 v170, v170
	v_rsq_f32_e32 v174, v174
	v_rsq_f32_e32 v178, v178
	v_rsq_f32_e32 v182, v182
	v_rsq_f32_e32 v186, v186
	v_rsq_f32_e32 v190, v190
	v_rsq_f32_e32 v194, v194
	v_rsq_f32_e32 v198, v198
	v_pk_add_f32 v[220:221], v[220:221], 1.0 op_sel_hi:[1,0]
	v_pk_add_f32 v[222:223], v[222:223], 1.0 op_sel_hi:[1,0]
	v_pk_add_f32 v[224:225], v[224:225], 1.0 op_sel_hi:[1,0]
	v_pk_add_f32 v[226:227], v[226:227], 1.0 op_sel_hi:[1,0]
	v_pk_add_f32 v[228:229], v[228:229], 1.0 op_sel_hi:[1,0]
	v_pk_add_f32 v[230:231], v[230:231], 1.0 op_sel_hi:[1,0]
	v_pk_add_f32 v[232:233], v[232:233], 1.0 op_sel_hi:[1,0]
	v_pk_add_f32 v[234:235], v[234:235], 1.0 op_sel_hi:[1,0]
	v_pk_mul_f32 v[132:133], v[132:133], v[170:171] op_sel_hi:[1,0]
	v_pk_mul_f32 v[134:135], v[134:135], v[170:171] op_sel_hi:[1,0]
	v_pk_mul_f32 v[128:129], v[128:129], v[170:171] op_sel_hi:[1,0]
	v_pk_mul_f32 v[130:131], v[130:131], v[170:171] op_sel_hi:[1,0]
	v_pk_mul_f32 v[132:133], v[204:205], v[132:133]
	v_pk_mul_f32 v[134:135], v[206:207], v[134:135]
	v_pk_mul_f32 v[128:129], v[208:209], v[128:129]
	v_pk_mul_f32 v[130:131], v[210:211], v[130:131]
	v_pk_fma_f32 v[132:133], v[220:221], v[132:133], v[236:237]
	v_pk_fma_f32 v[134:135], v[222:223], v[134:135], v[238:239]
	v_pk_fma_f32 v[128:129], v[224:225], v[128:129], v[146:147]
	v_pk_fma_f32 v[130:131], v[226:227], v[130:131], v[148:149]
	v_cvt_pk_bf16_f32 v132, v132, v133
	v_cvt_pk_bf16_f32 v133, v134, v135
	v_cvt_pk_bf16_f32 v134, v128, v129
	v_cvt_pk_bf16_f32 v135, v130, v131
	global_store_dwordx4 v144, v[132:135], s[14:15]
	v_pk_mul_f32 v[60:61], v[60:61], v[170:171] op_sel_hi:[1,0]
	v_pk_mul_f32 v[62:63], v[62:63], v[170:171] op_sel_hi:[1,0]
	v_pk_mul_f32 v[56:57], v[56:57], v[170:171] op_sel_hi:[1,0]
	v_pk_mul_f32 v[58:59], v[58:59], v[170:171] op_sel_hi:[1,0]
	v_pk_mul_f32 v[60:61], v[212:213], v[60:61]
	v_pk_mul_f32 v[62:63], v[214:215], v[62:63]
	v_pk_mul_f32 v[56:57], v[216:217], v[56:57]
	v_pk_mul_f32 v[58:59], v[218:219], v[58:59]
	v_pk_fma_f32 v[60:61], v[228:229], v[60:61], v[150:151]
	v_pk_fma_f32 v[62:63], v[230:231], v[62:63], v[152:153]
	v_pk_fma_f32 v[56:57], v[232:233], v[56:57], v[162:163]
	v_pk_fma_f32 v[58:59], v[234:235], v[58:59], v[164:165]
	v_cvt_pk_bf16_f32 v60, v60, v61
	v_cvt_pk_bf16_f32 v61, v62, v63
	v_cvt_pk_bf16_f32 v62, v56, v57
	v_cvt_pk_bf16_f32 v63, v58, v59
	global_store_dwordx4 v144, v[60:63], s[14:15] offset:256
	s_add_u32 s14, s14, 0x8000
	s_addc_u32 s15, s15, 0
	v_pk_mul_f32 v[124:125], v[124:125], v[174:175] op_sel_hi:[1,0]
	v_pk_mul_f32 v[126:127], v[126:127], v[174:175] op_sel_hi:[1,0]
	v_pk_mul_f32 v[120:121], v[120:121], v[174:175] op_sel_hi:[1,0]
	v_pk_mul_f32 v[122:123], v[122:123], v[174:175] op_sel_hi:[1,0]
	v_pk_mul_f32 v[124:125], v[204:205], v[124:125]
	v_pk_mul_f32 v[126:127], v[206:207], v[126:127]
	v_pk_mul_f32 v[120:121], v[208:209], v[120:121]
	v_pk_mul_f32 v[122:123], v[210:211], v[122:123]
	v_pk_fma_f32 v[124:125], v[220:221], v[124:125], v[236:237]
	v_pk_fma_f32 v[126:127], v[222:223], v[126:127], v[238:239]
	v_pk_fma_f32 v[120:121], v[224:225], v[120:121], v[146:147]
	v_pk_fma_f32 v[122:123], v[226:227], v[122:123], v[148:149]
	v_cvt_pk_bf16_f32 v124, v124, v125
	v_cvt_pk_bf16_f32 v125, v126, v127
	v_cvt_pk_bf16_f32 v126, v120, v121
	v_cvt_pk_bf16_f32 v127, v122, v123
	global_store_dwordx4 v144, v[124:127], s[14:15]
	v_pk_mul_f32 v[52:53], v[52:53], v[174:175] op_sel_hi:[1,0]
	v_pk_mul_f32 v[54:55], v[54:55], v[174:175] op_sel_hi:[1,0]
	v_pk_mul_f32 v[48:49], v[48:49], v[174:175] op_sel_hi:[1,0]
	v_pk_mul_f32 v[50:51], v[50:51], v[174:175] op_sel_hi:[1,0]
	v_pk_mul_f32 v[52:53], v[212:213], v[52:53]
	v_pk_mul_f32 v[54:55], v[214:215], v[54:55]
	v_pk_mul_f32 v[48:49], v[216:217], v[48:49]
	v_pk_mul_f32 v[50:51], v[218:219], v[50:51]
	v_pk_fma_f32 v[52:53], v[228:229], v[52:53], v[150:151]
	v_pk_fma_f32 v[54:55], v[230:231], v[54:55], v[152:153]
	v_pk_fma_f32 v[48:49], v[232:233], v[48:49], v[162:163]
	v_pk_fma_f32 v[50:51], v[234:235], v[50:51], v[164:165]
	v_cvt_pk_bf16_f32 v52, v52, v53
	v_cvt_pk_bf16_f32 v53, v54, v55
	v_cvt_pk_bf16_f32 v54, v48, v49
	v_cvt_pk_bf16_f32 v55, v50, v51
	global_store_dwordx4 v144, v[52:55], s[14:15] offset:256
	s_add_u32 s14, s14, 0x8000
	s_addc_u32 s15, s15, 0
	v_pk_mul_f32 v[116:117], v[116:117], v[178:179] op_sel_hi:[1,0]
	v_pk_mul_f32 v[118:119], v[118:119], v[178:179] op_sel_hi:[1,0]
	v_pk_mul_f32 v[112:113], v[112:113], v[178:179] op_sel_hi:[1,0]
	v_pk_mul_f32 v[114:115], v[114:115], v[178:179] op_sel_hi:[1,0]
	v_pk_mul_f32 v[116:117], v[204:205], v[116:117]
	v_pk_mul_f32 v[118:119], v[206:207], v[118:119]
	v_pk_mul_f32 v[112:113], v[208:209], v[112:113]
	v_pk_mul_f32 v[114:115], v[210:211], v[114:115]
	v_pk_fma_f32 v[116:117], v[220:221], v[116:117], v[236:237]
	v_pk_fma_f32 v[118:119], v[222:223], v[118:119], v[238:239]
	v_pk_fma_f32 v[112:113], v[224:225], v[112:113], v[146:147]
	v_pk_fma_f32 v[114:115], v[226:227], v[114:115], v[148:149]
	v_cvt_pk_bf16_f32 v116, v116, v117
	v_cvt_pk_bf16_f32 v117, v118, v119
	v_cvt_pk_bf16_f32 v118, v112, v113
	v_cvt_pk_bf16_f32 v119, v114, v115
	global_store_dwordx4 v144, v[116:119], s[14:15]
	v_pk_mul_f32 v[44:45], v[44:45], v[178:179] op_sel_hi:[1,0]
	v_pk_mul_f32 v[46:47], v[46:47], v[178:179] op_sel_hi:[1,0]
	v_pk_mul_f32 v[40:41], v[40:41], v[178:179] op_sel_hi:[1,0]
	v_pk_mul_f32 v[42:43], v[42:43], v[178:179] op_sel_hi:[1,0]
	v_pk_mul_f32 v[44:45], v[212:213], v[44:45]
	v_pk_mul_f32 v[46:47], v[214:215], v[46:47]
	v_pk_mul_f32 v[40:41], v[216:217], v[40:41]
	v_pk_mul_f32 v[42:43], v[218:219], v[42:43]
	v_pk_fma_f32 v[44:45], v[228:229], v[44:45], v[150:151]
	v_pk_fma_f32 v[46:47], v[230:231], v[46:47], v[152:153]
	v_pk_fma_f32 v[40:41], v[232:233], v[40:41], v[162:163]
	v_pk_fma_f32 v[42:43], v[234:235], v[42:43], v[164:165]
	v_cvt_pk_bf16_f32 v44, v44, v45
	v_cvt_pk_bf16_f32 v45, v46, v47
	v_cvt_pk_bf16_f32 v46, v40, v41
	v_cvt_pk_bf16_f32 v47, v42, v43
	global_store_dwordx4 v144, v[44:47], s[14:15] offset:256
	s_add_u32 s14, s14, 0x8000
	s_addc_u32 s15, s15, 0
	v_pk_mul_f32 v[108:109], v[108:109], v[182:183] op_sel_hi:[1,0]
	v_pk_mul_f32 v[110:111], v[110:111], v[182:183] op_sel_hi:[1,0]
	v_pk_mul_f32 v[104:105], v[104:105], v[182:183] op_sel_hi:[1,0]
	v_pk_mul_f32 v[106:107], v[106:107], v[182:183] op_sel_hi:[1,0]
	v_pk_mul_f32 v[108:109], v[204:205], v[108:109]
	v_pk_mul_f32 v[110:111], v[206:207], v[110:111]
	v_pk_mul_f32 v[104:105], v[208:209], v[104:105]
	v_pk_mul_f32 v[106:107], v[210:211], v[106:107]
	v_pk_fma_f32 v[108:109], v[220:221], v[108:109], v[236:237]
	v_pk_fma_f32 v[110:111], v[222:223], v[110:111], v[238:239]
	v_pk_fma_f32 v[104:105], v[224:225], v[104:105], v[146:147]
	v_pk_fma_f32 v[106:107], v[226:227], v[106:107], v[148:149]
	v_cvt_pk_bf16_f32 v108, v108, v109
	v_cvt_pk_bf16_f32 v109, v110, v111
	v_cvt_pk_bf16_f32 v110, v104, v105
	v_cvt_pk_bf16_f32 v111, v106, v107
	global_store_dwordx4 v144, v[108:111], s[14:15]
	v_pk_mul_f32 v[32:33], v[32:33], v[182:183] op_sel_hi:[1,0]
	v_pk_mul_f32 v[34:35], v[34:35], v[182:183] op_sel_hi:[1,0]
	v_pk_mul_f32 v[24:25], v[24:25], v[182:183] op_sel_hi:[1,0]
	v_pk_mul_f32 v[26:27], v[26:27], v[182:183] op_sel_hi:[1,0]
	v_pk_mul_f32 v[32:33], v[212:213], v[32:33]
	v_pk_mul_f32 v[34:35], v[214:215], v[34:35]
	v_pk_mul_f32 v[24:25], v[216:217], v[24:25]
	v_pk_mul_f32 v[26:27], v[218:219], v[26:27]
	v_pk_fma_f32 v[32:33], v[228:229], v[32:33], v[150:151]
	v_pk_fma_f32 v[34:35], v[230:231], v[34:35], v[152:153]
	v_pk_fma_f32 v[24:25], v[232:233], v[24:25], v[162:163]
	v_pk_fma_f32 v[26:27], v[234:235], v[26:27], v[164:165]
	v_cvt_pk_bf16_f32 v32, v32, v33
	v_cvt_pk_bf16_f32 v33, v34, v35
	v_cvt_pk_bf16_f32 v34, v24, v25
	v_cvt_pk_bf16_f32 v35, v26, v27
	global_store_dwordx4 v144, v[32:35], s[14:15] offset:256
	s_add_u32 s14, s14, 0x28000
	s_addc_u32 s15, s15, 0
	v_pk_mul_f32 v[100:101], v[100:101], v[186:187] op_sel_hi:[1,0]
	v_pk_mul_f32 v[102:103], v[102:103], v[186:187] op_sel_hi:[1,0]
	v_pk_mul_f32 v[96:97], v[96:97], v[186:187] op_sel_hi:[1,0]
	v_pk_mul_f32 v[98:99], v[98:99], v[186:187] op_sel_hi:[1,0]
	v_pk_mul_f32 v[100:101], v[204:205], v[100:101]
	v_pk_mul_f32 v[102:103], v[206:207], v[102:103]
	v_pk_mul_f32 v[96:97], v[208:209], v[96:97]
	v_pk_mul_f32 v[98:99], v[210:211], v[98:99]
	v_pk_fma_f32 v[100:101], v[220:221], v[100:101], v[236:237]
	v_pk_fma_f32 v[102:103], v[222:223], v[102:103], v[238:239]
	v_pk_fma_f32 v[96:97], v[224:225], v[96:97], v[146:147]
	v_pk_fma_f32 v[98:99], v[226:227], v[98:99], v[148:149]
	v_cvt_pk_bf16_f32 v100, v100, v101
	v_cvt_pk_bf16_f32 v101, v102, v103
	v_cvt_pk_bf16_f32 v102, v96, v97
	v_cvt_pk_bf16_f32 v103, v98, v99
	global_store_dwordx4 v144, v[100:103], s[14:15]
	v_pk_mul_f32 v[36:37], v[36:37], v[186:187] op_sel_hi:[1,0]
	v_pk_mul_f32 v[38:39], v[38:39], v[186:187] op_sel_hi:[1,0]
	v_pk_mul_f32 v[28:29], v[28:29], v[186:187] op_sel_hi:[1,0]
	v_pk_mul_f32 v[30:31], v[30:31], v[186:187] op_sel_hi:[1,0]
	v_pk_mul_f32 v[36:37], v[212:213], v[36:37]
	v_pk_mul_f32 v[38:39], v[214:215], v[38:39]
	v_pk_mul_f32 v[28:29], v[216:217], v[28:29]
	v_pk_mul_f32 v[30:31], v[218:219], v[30:31]
	v_pk_fma_f32 v[36:37], v[228:229], v[36:37], v[150:151]
	v_pk_fma_f32 v[38:39], v[230:231], v[38:39], v[152:153]
	v_pk_fma_f32 v[28:29], v[232:233], v[28:29], v[162:163]
	v_pk_fma_f32 v[30:31], v[234:235], v[30:31], v[164:165]
	v_cvt_pk_bf16_f32 v36, v36, v37
	v_cvt_pk_bf16_f32 v37, v38, v39
	v_cvt_pk_bf16_f32 v38, v28, v29
	v_cvt_pk_bf16_f32 v39, v30, v31
	global_store_dwordx4 v144, v[36:39], s[14:15] offset:256
	s_add_u32 s14, s14, 0x8000
	s_addc_u32 s15, s15, 0
	v_pk_mul_f32 v[92:93], v[92:93], v[190:191] op_sel_hi:[1,0]
	v_pk_mul_f32 v[94:95], v[94:95], v[190:191] op_sel_hi:[1,0]
	v_pk_mul_f32 v[88:89], v[88:89], v[190:191] op_sel_hi:[1,0]
	v_pk_mul_f32 v[90:91], v[90:91], v[190:191] op_sel_hi:[1,0]
	v_pk_mul_f32 v[92:93], v[204:205], v[92:93]
	v_pk_mul_f32 v[94:95], v[206:207], v[94:95]
	v_pk_mul_f32 v[88:89], v[208:209], v[88:89]
	v_pk_mul_f32 v[90:91], v[210:211], v[90:91]
	v_pk_fma_f32 v[92:93], v[220:221], v[92:93], v[236:237]
	v_pk_fma_f32 v[94:95], v[222:223], v[94:95], v[238:239]
	v_pk_fma_f32 v[88:89], v[224:225], v[88:89], v[146:147]
	v_pk_fma_f32 v[90:91], v[226:227], v[90:91], v[148:149]
	v_cvt_pk_bf16_f32 v92, v92, v93
	v_cvt_pk_bf16_f32 v93, v94, v95
	v_cvt_pk_bf16_f32 v94, v88, v89
	v_cvt_pk_bf16_f32 v95, v90, v91
	global_store_dwordx4 v144, v[92:95], s[14:15]
	v_pk_mul_f32 v[20:21], v[20:21], v[190:191] op_sel_hi:[1,0]
	v_pk_mul_f32 v[22:23], v[22:23], v[190:191] op_sel_hi:[1,0]
	v_pk_mul_f32 v[16:17], v[16:17], v[190:191] op_sel_hi:[1,0]
	v_pk_mul_f32 v[18:19], v[18:19], v[190:191] op_sel_hi:[1,0]
	v_pk_mul_f32 v[20:21], v[212:213], v[20:21]
	v_pk_mul_f32 v[22:23], v[214:215], v[22:23]
	v_pk_mul_f32 v[16:17], v[216:217], v[16:17]
	v_pk_mul_f32 v[18:19], v[218:219], v[18:19]
	v_pk_fma_f32 v[20:21], v[228:229], v[20:21], v[150:151]
	v_pk_fma_f32 v[22:23], v[230:231], v[22:23], v[152:153]
	v_pk_fma_f32 v[16:17], v[232:233], v[16:17], v[162:163]
	v_pk_fma_f32 v[18:19], v[234:235], v[18:19], v[164:165]
	v_cvt_pk_bf16_f32 v20, v20, v21
	v_cvt_pk_bf16_f32 v21, v22, v23
	v_cvt_pk_bf16_f32 v22, v16, v17
	v_cvt_pk_bf16_f32 v23, v18, v19
	global_store_dwordx4 v144, v[20:23], s[14:15] offset:256
	s_add_u32 s14, s14, 0x8000
	s_addc_u32 s15, s15, 0
	v_pk_mul_f32 v[84:85], v[84:85], v[194:195] op_sel_hi:[1,0]
	v_pk_mul_f32 v[86:87], v[86:87], v[194:195] op_sel_hi:[1,0]
	v_pk_mul_f32 v[80:81], v[80:81], v[194:195] op_sel_hi:[1,0]
	v_pk_mul_f32 v[82:83], v[82:83], v[194:195] op_sel_hi:[1,0]
	v_pk_mul_f32 v[84:85], v[204:205], v[84:85]
	v_pk_mul_f32 v[86:87], v[206:207], v[86:87]
	v_pk_mul_f32 v[80:81], v[208:209], v[80:81]
	v_pk_mul_f32 v[82:83], v[210:211], v[82:83]
	v_pk_fma_f32 v[84:85], v[220:221], v[84:85], v[236:237]
	v_pk_fma_f32 v[86:87], v[222:223], v[86:87], v[238:239]
	v_pk_fma_f32 v[80:81], v[224:225], v[80:81], v[146:147]
	v_pk_fma_f32 v[82:83], v[226:227], v[82:83], v[148:149]
	v_cvt_pk_bf16_f32 v84, v84, v85
	v_cvt_pk_bf16_f32 v85, v86, v87
	v_cvt_pk_bf16_f32 v86, v80, v81
	v_cvt_pk_bf16_f32 v87, v82, v83
	global_store_dwordx4 v144, v[84:87], s[14:15]
	v_pk_mul_f32 v[12:13], v[12:13], v[194:195] op_sel_hi:[1,0]
	v_pk_mul_f32 v[14:15], v[14:15], v[194:195] op_sel_hi:[1,0]
	v_pk_mul_f32 v[8:9], v[8:9], v[194:195] op_sel_hi:[1,0]
	v_pk_mul_f32 v[10:11], v[10:11], v[194:195] op_sel_hi:[1,0]
	v_pk_mul_f32 v[12:13], v[212:213], v[12:13]
	v_pk_mul_f32 v[14:15], v[214:215], v[14:15]
	v_pk_mul_f32 v[8:9], v[216:217], v[8:9]
	v_pk_mul_f32 v[10:11], v[218:219], v[10:11]
	v_pk_fma_f32 v[12:13], v[228:229], v[12:13], v[150:151]
	v_pk_fma_f32 v[14:15], v[230:231], v[14:15], v[152:153]
	v_pk_fma_f32 v[8:9], v[232:233], v[8:9], v[162:163]
	v_pk_fma_f32 v[10:11], v[234:235], v[10:11], v[164:165]
	v_cvt_pk_bf16_f32 v12, v12, v13
	v_cvt_pk_bf16_f32 v13, v14, v15
	v_cvt_pk_bf16_f32 v14, v8, v9
	v_cvt_pk_bf16_f32 v15, v10, v11
	global_store_dwordx4 v144, v[12:15], s[14:15] offset:256
	s_add_u32 s14, s14, 0x8000
	s_addc_u32 s15, s15, 0
	v_pk_mul_f32 v[68:69], v[68:69], v[198:199] op_sel_hi:[1,0]
	v_pk_mul_f32 v[70:71], v[70:71], v[198:199] op_sel_hi:[1,0]
	v_pk_mul_f32 v[64:65], v[64:65], v[198:199] op_sel_hi:[1,0]
	v_pk_mul_f32 v[66:67], v[66:67], v[198:199] op_sel_hi:[1,0]
	v_pk_mul_f32 v[68:69], v[204:205], v[68:69]
	v_pk_mul_f32 v[70:71], v[206:207], v[70:71]
	v_pk_mul_f32 v[64:65], v[208:209], v[64:65]
	v_pk_mul_f32 v[66:67], v[210:211], v[66:67]
	v_pk_fma_f32 v[68:69], v[220:221], v[68:69], v[236:237]
	v_pk_fma_f32 v[70:71], v[222:223], v[70:71], v[238:239]
	v_pk_fma_f32 v[64:65], v[224:225], v[64:65], v[146:147]
	v_pk_fma_f32 v[66:67], v[226:227], v[66:67], v[148:149]
	v_cvt_pk_bf16_f32 v68, v68, v69
	v_cvt_pk_bf16_f32 v69, v70, v71
	v_cvt_pk_bf16_f32 v70, v64, v65
	v_cvt_pk_bf16_f32 v71, v66, v67
	global_store_dwordx4 v144, v[68:71], s[14:15]
	v_pk_mul_f32 v[246:247], v[246:247], v[198:199] op_sel_hi:[1,0]
	v_pk_mul_f32 v[248:249], v[248:249], v[198:199] op_sel_hi:[1,0]
	v_pk_mul_f32 v[242:243], v[242:243], v[198:199] op_sel_hi:[1,0]
	v_pk_mul_f32 v[244:245], v[244:245], v[198:199] op_sel_hi:[1,0]
	v_pk_mul_f32 v[246:247], v[212:213], v[246:247]
	v_pk_mul_f32 v[248:249], v[214:215], v[248:249]
	v_pk_mul_f32 v[242:243], v[216:217], v[242:243]
	v_pk_mul_f32 v[244:245], v[218:219], v[244:245]
	v_pk_fma_f32 v[246:247], v[228:229], v[246:247], v[150:151]
	v_pk_fma_f32 v[248:249], v[230:231], v[248:249], v[152:153]
	v_pk_fma_f32 v[242:243], v[232:233], v[242:243], v[162:163]
	v_pk_fma_f32 v[244:245], v[234:235], v[244:245], v[164:165]
	v_cvt_pk_bf16_f32 v246, v246, v247
	v_cvt_pk_bf16_f32 v247, v248, v249
	v_cvt_pk_bf16_f32 v248, v242, v243
	v_cvt_pk_bf16_f32 v249, v244, v245
	global_store_dwordx4 v144, v[246:249], s[14:15] offset:256
	s_branch .LBB0_189
	v_readlane_b32 s0, v253, 0
	v_readfirstlane_b32 s1, v2
	s_ashr_i32 s1, s1, 6
	s_lshl_b32 s0, s0, 3
	s_and_b32 s1, s1, -4
	v_lshrrev_b32_e32 v1, 6, v0
	s_add_i32 s1, s1, s0
	v_and_or_b32 v16, v1, 3, s1
	s_movk_i32 s0, 0x4000
	v_cmp_gt_i32_e32 vcc, s0, v16
	s_and_saveexec_b64 s[0:1], vcc
	v_readlane_b32 s8, v254, 47
	v_readlane_b32 s10, v254, 49
	s_movk_i32 s6, 0x3fff
	v_readlane_b32 s9, v254, 48
	v_readlane_b32 s11, v254, 50
	s_cbranch_execz .LBB0_189
	v_readlane_b32 s4, v254, 58
	v_readlane_b32 s5, v254, 59
	v_readlane_b32 s36, v253, 11
	s_lshl_b64 s[4:5], s[4:5], 2
	v_readlane_b32 s50, v253, 25
	v_readlane_b32 s51, v253, 26
	s_add_u32 s4, s50, s4
	v_and_b32_e32 v2, 63, v0
	s_addc_u32 s5, s51, s5
	v_lshlrev_b32_e32 v136, 5, v2
	v_lshl_add_u64 v[18:19], s[4:5], 0, v[136:137]
	v_readlane_b32 s4, v254, 55
	v_lshlrev_b32_e32 v0, 2, v2
	v_readlane_b32 s5, v254, 56
	v_xor_b32_e32 v29, 64, v0
	v_xor_b32_e32 v34, 0x80, v0
	v_lshl_add_u64 v[0:1], s[4:5], 0, v[136:137]
	s_mov_b64 s[4:5], 0x4000
	v_lshl_add_u64 v[20:21], v[0:1], 0, s[4:5]
	s_mov_b64 s[4:5], 0x3000
	v_ashrrev_i32_e32 v17, 31, v16
	v_lshl_add_u64 v[22:23], v[0:1], 0, s[4:5]
	v_lshlrev_b64 v[0:1], 11, v[16:17]
	v_readlane_b32 s4, v253, 47
	v_lshl_or_b32 v0, v2, 4, v0
	v_readlane_b32 s5, v253, 48
	v_readlane_b32 s37, v253, 12
	v_readlane_b32 s38, v253, 13
	v_lshl_add_u64 v[24:25], s[4:5], 0, v[0:1]
	v_lshlrev_b64 v[0:1], 12, v[16:17]
	v_or_b32_e32 v0, v0, v136
	v_lshl_add_u64 v[26:27], s[70:71], 0, v[0:1]
	s_mov_b64 s[4:5], 0
	v_readlane_b32 s39, v253, 14
	v_readlane_b32 s40, v253, 15
	v_readlane_b32 s41, v253, 16
	v_readlane_b32 s42, v253, 17
	v_readlane_b32 s43, v253, 18
	v_readlane_b32 s44, v253, 19
	v_readlane_b32 s45, v253, 20
	v_readlane_b32 s46, v253, 21
	v_readlane_b32 s47, v253, 22
	v_readlane_b32 s48, v253, 23
	v_readlane_b32 s49, v253, 24

.LBB0_587:
	s_or_b64 exec, exec, s[4:5]
	v_mov_b32_e32 v80, v154
	s_lshl_b32 s4, s15, 8
	v_and_b32_e32 v136, 15, v80
	v_lshrrev_b32_e32 v81, 1, v80
	v_ashrrev_i32_e32 v80, 2, v80
	v_and_b32_e32 v152, 0xffffffc0, v80
	v_ashrrev_i32_e32 v153, 31, v152
	s_mov_b32 s5, s52
	s_lshr_b32 s1, s14, 3
	v_and_b32_e32 v81, 0x78, v81
	v_lshl_add_u64 v[140:141], v[152:153], 0, s[4:5]
	v_lshl_or_b32 v144, s0, 8, v81
	s_mul_i32 s1, s1, 0x9000
	v_or_b32_e32 v140, v140, v136
	s_add_u32 s0, s11, s1
	v_ashrrev_i32_e32 v145, 31, v144
	v_lshlrev_b64 v[140:141], 12, v[140:141]
	s_addc_u32 s1, s12, 0
	v_lshlrev_b64 v[150:151], 2, v[144:145]
	v_lshl_add_u64 v[170:171], s[70:71], 0, v[140:141]
	v_lshl_add_u64 v[146:147], s[0:1], 0, v[150:151]
	v_lshl_add_u64 v[148:149], v[170:171], 0, v[150:151]
	s_nop 1
	v_readfirstlane_b32 s38, v148
	v_readfirstlane_b32 s39, v149
	s_nop 1
	v_subrev_u32_e32 v139, s38, v148
	s_mov_b64 s[40:41], s[38:39]
	s_mov_b64 s[42:43], s[38:39]
	s_mov_b64 s[44:45], s[40:41]
	s_mov_b64 s[46:47], s[42:43]
	s_mov_b64 s[36:37], 0x20000
	global_load_dwordx4 v[234:237], v[146:147], off
	global_load_dwordx4 v[238:241], v[146:147], off offset:16
	global_load_dwordx4 v[242:245], v[146:147], off offset:512
	global_load_dwordx4 v[246:249], v[146:147], off offset:528
	global_load_dwordx4 v[178:181], v139, s[40:41]
	global_load_dwordx4 v[182:185], v139, s[40:41] offset:16
	s_add_u32 s40, s40, 0x10000
	s_addc_u32 s41, s41, 0
	global_load_dwordx4 v[186:189], v139, s[40:41]
	global_load_dwordx4 v[190:193], v139, s[40:41] offset:16
	s_add_u32 s40, s40, 0x10000
	s_addc_u32 s41, s41, 0
	global_load_dwordx4 v[194:197], v139, s[40:41]
	global_load_dwordx4 v[198:201], v139, s[40:41] offset:16
	s_add_u32 s40, s40, 0x10000
	s_addc_u32 s41, s41, 0
	global_load_dwordx4 v[202:205], v139, s[40:41]
	global_load_dwordx4 v[206:209], v139, s[40:41] offset:16
	s_add_u32 s40, s40, 0x50000
	s_addc_u32 s41, s41, 0
	global_load_dwordx4 v[210:213], v139, s[40:41]
	global_load_dwordx4 v[214:217], v139, s[40:41] offset:16
	s_add_u32 s40, s40, 0x10000
	s_addc_u32 s41, s41, 0
	global_load_dwordx4 v[218:221], v139, s[40:41]
	global_load_dwordx4 v[222:225], v139, s[40:41] offset:16
	s_add_u32 s40, s40, 0x10000
	s_addc_u32 s41, s41, 0
	global_load_dwordx4 v[226:229], v139, s[40:41]
	global_load_dwordx4 v[230:233], v139, s[40:41] offset:16
	s_add_u32 s40, s40, 0x10000
	s_addc_u32 s41, s41, 0
	s_waitcnt vmcnt(12)
	v_pk_fma_f32 v[128:129], v[128:129], v[234:235], v[178:179]
	v_pk_fma_f32 v[130:131], v[130:131], v[236:237], v[180:181]
	v_pk_fma_f32 v[132:133], v[132:133], v[238:239], v[182:183]
	v_pk_fma_f32 v[134:135], v[134:135], v[240:241], v[184:185]
	global_store_dwordx4 v139, v[128:131], s[42:43]
	global_store_dwordx4 v139, v[132:135], s[42:43] offset:16
	s_add_u32 s42, s42, 0x10000
	s_addc_u32 s43, s43, 0
	global_load_dwordx4 v[178:181], v139, s[40:41]
	global_load_dwordx4 v[182:185], v139, s[40:41] offset:16
	s_mov_b64 s[40:41], s[44:45]
	s_waitcnt vmcnt(14)
	v_pk_fma_f32 v[124:125], v[124:125], v[234:235], v[186:187]
	v_pk_fma_f32 v[126:127], v[126:127], v[236:237], v[188:189]
	v_pk_fma_f32 v[120:121], v[120:121], v[238:239], v[190:191]
	v_pk_fma_f32 v[122:123], v[122:123], v[240:241], v[192:193]
	global_store_dwordx4 v139, v[124:127], s[42:43]
	global_store_dwordx4 v139, v[120:123], s[42:43] offset:16
	s_add_u32 s42, s42, 0x10000
	s_addc_u32 s43, s43, 0
	global_load_dwordx4 v[186:189], v139, s[40:41] offset:512
	global_load_dwordx4 v[190:193], v139, s[40:41] offset:528
	s_add_u32 s40, s40, 0x10000
	s_addc_u32 s41, s41, 0
	s_waitcnt vmcnt(16)
	v_pk_fma_f32 v[112:113], v[112:113], v[234:235], v[194:195]
	v_pk_fma_f32 v[114:115], v[114:115], v[236:237], v[196:197]
	v_pk_fma_f32 v[116:117], v[116:117], v[238:239], v[198:199]
	v_pk_fma_f32 v[118:119], v[118:119], v[240:241], v[200:201]
	global_store_dwordx4 v139, v[112:115], s[42:43]
	global_store_dwordx4 v139, v[116:119], s[42:43] offset:16
	s_add_u32 s42, s42, 0x10000
	s_addc_u32 s43, s43, 0
	global_load_dwordx4 v[194:197], v139, s[40:41] offset:512
	global_load_dwordx4 v[198:201], v139, s[40:41] offset:528
	s_add_u32 s40, s40, 0x10000
	s_addc_u32 s41, s41, 0
	s_waitcnt vmcnt(18)
	v_pk_fma_f32 v[100:101], v[100:101], v[234:235], v[202:203]
	v_pk_fma_f32 v[102:103], v[102:103], v[236:237], v[204:205]
	v_pk_fma_f32 v[96:97], v[96:97], v[238:239], v[206:207]
	v_pk_fma_f32 v[98:99], v[98:99], v[240:241], v[208:209]
	global_store_dwordx4 v139, v[100:103], s[42:43]
	global_store_dwordx4 v139, v[96:99], s[42:43] offset:16
	s_add_u32 s42, s42, 0x50000
	s_addc_u32 s43, s43, 0
	global_load_dwordx4 v[202:205], v139, s[40:41] offset:512
	global_load_dwordx4 v[206:209], v139, s[40:41] offset:528
	s_add_u32 s40, s40, 0x10000
	s_addc_u32 s41, s41, 0
	s_waitcnt vmcnt(20)
	v_pk_fma_f32 v[104:105], v[104:105], v[234:235], v[210:211]
	v_pk_fma_f32 v[106:107], v[106:107], v[236:237], v[212:213]
	v_pk_fma_f32 v[108:109], v[108:109], v[238:239], v[214:215]
	v_pk_fma_f32 v[110:111], v[110:111], v[240:241], v[216:217]
	global_store_dwordx4 v139, v[104:107], s[42:43]
	global_store_dwordx4 v139, v[108:111], s[42:43] offset:16
	s_add_u32 s42, s42, 0x10000
	s_addc_u32 s43, s43, 0
	global_load_dwordx4 v[210:213], v139, s[40:41] offset:512
	global_load_dwordx4 v[214:217], v139, s[40:41] offset:528
	s_add_u32 s40, s40, 0x50000
	s_addc_u32 s41, s41, 0
	s_waitcnt vmcnt(22)
	v_pk_fma_f32 v[92:93], v[92:93], v[234:235], v[218:219]
	v_pk_fma_f32 v[94:95], v[94:95], v[236:237], v[220:221]
	v_pk_fma_f32 v[84:85], v[84:85], v[238:239], v[222:223]
	v_pk_fma_f32 v[86:87], v[86:87], v[240:241], v[224:225]
	global_store_dwordx4 v139, v[92:95], s[42:43]
	global_store_dwordx4 v139, v[84:87], s[42:43] offset:16
	s_add_u32 s42, s42, 0x10000
	s_addc_u32 s43, s43, 0
	global_load_dwordx4 v[218:221], v139, s[40:41] offset:512
	global_load_dwordx4 v[222:225], v139, s[40:41] offset:528
	s_add_u32 s40, s40, 0x10000
	s_addc_u32 s41, s41, 0
	s_waitcnt vmcnt(24)
	v_pk_fma_f32 v[72:73], v[72:73], v[234:235], v[226:227]
	v_pk_fma_f32 v[74:75], v[74:75], v[236:237], v[228:229]
	v_pk_fma_f32 v[76:77], v[76:77], v[238:239], v[230:231]
	v_pk_fma_f32 v[78:79], v[78:79], v[240:241], v[232:233]
	global_store_dwordx4 v139, v[72:75], s[42:43]
	global_store_dwordx4 v139, v[76:79], s[42:43] offset:16
	s_add_u32 s42, s42, 0x10000
	s_addc_u32 s43, s43, 0
	global_load_dwordx4 v[226:229], v139, s[40:41] offset:512
	global_load_dwordx4 v[230:233], v139, s[40:41] offset:528
	s_add_u32 s40, s40, 0x10000
	s_addc_u32 s41, s41, 0
	s_waitcnt vmcnt(24)
	v_pk_fma_f32 v[68:69], v[68:69], v[234:235], v[178:179]
	v_pk_fma_f32 v[70:71], v[70:71], v[236:237], v[180:181]
	v_pk_fma_f32 v[64:65], v[64:65], v[238:239], v[182:183]
	v_pk_fma_f32 v[66:67], v[66:67], v[240:241], v[184:185]
	global_store_dwordx4 v139, v[68:71], s[42:43]
	global_store_dwordx4 v139, v[64:67], s[42:43] offset:16
	s_mov_b64 s[42:43], s[46:47]
	global_load_dwordx4 v[178:181], v139, s[40:41] offset:512
	global_load_dwordx4 v[182:185], v139, s[40:41] offset:528
	s_add_u32 s40, s40, 0x10000
	s_addc_u32 s41, s41, 0
	s_waitcnt vmcnt(24)
	v_pk_fma_f32 v[56:57], v[56:57], v[242:243], v[186:187]
	v_pk_fma_f32 v[58:59], v[58:59], v[244:245], v[188:189]
	v_pk_fma_f32 v[60:61], v[60:61], v[246:247], v[190:191]
	v_pk_fma_f32 v[62:63], v[62:63], v[248:249], v[192:193]
	global_store_dwordx4 v139, v[56:59], s[42:43] offset:512
	global_store_dwordx4 v139, v[60:63], s[42:43] offset:528
	s_add_u32 s42, s42, 0x10000
	s_addc_u32 s43, s43, 0
	global_load_dwordx4 v[186:189], v139, s[40:41] offset:512
	global_load_dwordx4 v[190:193], v139, s[40:41] offset:528
	s_waitcnt vmcnt(24)
	v_pk_fma_f32 v[52:53], v[52:53], v[242:243], v[194:195]
	v_pk_fma_f32 v[54:55], v[54:55], v[244:245], v[196:197]
	v_pk_fma_f32 v[48:49], v[48:49], v[246:247], v[198:199]
	v_pk_fma_f32 v[50:51], v[50:51], v[248:249], v[200:201]
	global_store_dwordx4 v139, v[52:55], s[42:43] offset:512
	global_store_dwordx4 v139, v[48:51], s[42:43] offset:528
	s_add_u32 s42, s42, 0x10000
	s_addc_u32 s43, s43, 0
	s_waitcnt vmcnt(22)
	v_pk_fma_f32 v[40:41], v[40:41], v[242:243], v[202:203]
	v_pk_fma_f32 v[42:43], v[42:43], v[244:245], v[204:205]
	v_pk_fma_f32 v[44:45], v[44:45], v[246:247], v[206:207]
	v_pk_fma_f32 v[46:47], v[46:47], v[248:249], v[208:209]
	global_store_dwordx4 v139, v[40:43], s[42:43] offset:512
	global_store_dwordx4 v139, v[44:47], s[42:43] offset:528
	s_add_u32 s42, s42, 0x10000
	s_addc_u32 s43, s43, 0
	s_waitcnt vmcnt(20)
	v_pk_fma_f32 v[32:33], v[32:33], v[242:243], v[210:211]
	v_pk_fma_f32 v[34:35], v[34:35], v[244:245], v[212:213]
	v_pk_fma_f32 v[24:25], v[24:25], v[246:247], v[214:215]
	v_pk_fma_f32 v[26:27], v[26:27], v[248:249], v[216:217]
	global_store_dwordx4 v139, v[32:35], s[42:43] offset:512
	global_store_dwordx4 v139, v[24:27], s[42:43] offset:528
	s_add_u32 s42, s42, 0x50000
	s_addc_u32 s43, s43, 0
	s_waitcnt vmcnt(18)
	v_pk_fma_f32 v[36:37], v[36:37], v[242:243], v[218:219]
	v_pk_fma_f32 v[38:39], v[38:39], v[244:245], v[220:221]
	v_pk_fma_f32 v[28:29], v[28:29], v[246:247], v[222:223]
	v_pk_fma_f32 v[30:31], v[30:31], v[248:249], v[224:225]
	global_store_dwordx4 v139, v[36:39], s[42:43] offset:512
	global_store_dwordx4 v139, v[28:31], s[42:43] offset:528
	s_add_u32 s42, s42, 0x10000
	s_addc_u32 s43, s43, 0
	s_waitcnt vmcnt(16)
	v_pk_fma_f32 v[20:21], v[20:21], v[242:243], v[226:227]
	v_pk_fma_f32 v[22:23], v[22:23], v[244:245], v[228:229]
	v_pk_fma_f32 v[16:17], v[16:17], v[246:247], v[230:231]
	v_pk_fma_f32 v[18:19], v[18:19], v[248:249], v[232:233]
	global_store_dwordx4 v139, v[20:23], s[42:43] offset:512
	global_store_dwordx4 v139, v[16:19], s[42:43] offset:528
	s_add_u32 s42, s42, 0x10000
	s_addc_u32 s43, s43, 0
	s_waitcnt vmcnt(14)
	v_pk_fma_f32 v[12:13], v[12:13], v[242:243], v[178:179]
	v_pk_fma_f32 v[14:15], v[14:15], v[244:245], v[180:181]
	v_pk_fma_f32 v[8:9], v[8:9], v[246:247], v[182:183]
	v_pk_fma_f32 v[10:11], v[10:11], v[248:249], v[184:185]
	global_store_dwordx4 v139, v[12:15], s[42:43] offset:512
	global_store_dwordx4 v139, v[8:11], s[42:43] offset:528
	s_add_u32 s42, s42, 0x10000
	s_addc_u32 s43, s43, 0
	s_waitcnt vmcnt(12)
	v_pk_fma_f32 v[4:5], v[4:5], v[242:243], v[186:187]
	v_pk_fma_f32 v[6:7], v[6:7], v[244:245], v[188:189]
	v_pk_fma_f32 v[0:1], v[0:1], v[246:247], v[190:191]
	v_pk_fma_f32 v[2:3], v[2:3], v[248:249], v[192:193]
	global_store_dwordx4 v139, v[4:7], s[42:43] offset:512
	global_store_dwordx4 v139, v[0:3], s[42:43] offset:528
	v_pk_mul_f32 v[200:201], v[128:129], v[128:129]
	v_pk_mul_f32 v[202:203], v[124:125], v[124:125]
	v_pk_mul_f32 v[204:205], v[112:113], v[112:113]
	v_pk_mul_f32 v[206:207], v[100:101], v[100:101]
	v_pk_mul_f32 v[208:209], v[104:105], v[104:105]
	v_pk_mul_f32 v[210:211], v[92:93], v[92:93]
	v_pk_mul_f32 v[212:213], v[72:73], v[72:73]
	v_pk_mul_f32 v[214:215], v[68:69], v[68:69]
	v_pk_fma_f32 v[200:201], v[130:131], v[130:131], v[200:201]
	v_pk_fma_f32 v[202:203], v[126:127], v[126:127], v[202:203]
	v_pk_fma_f32 v[204:205], v[114:115], v[114:115], v[204:205]
	v_pk_fma_f32 v[206:207], v[102:103], v[102:103], v[206:207]
	v_pk_fma_f32 v[208:209], v[106:107], v[106:107], v[208:209]
	v_pk_fma_f32 v[210:211], v[94:95], v[94:95], v[210:211]
	v_pk_fma_f32 v[212:213], v[74:75], v[74:75], v[212:213]
	v_pk_fma_f32 v[214:215], v[70:71], v[70:71], v[214:215]
	v_pk_fma_f32 v[200:201], v[132:133], v[132:133], v[200:201]
	v_pk_fma_f32 v[202:203], v[120:121], v[120:121], v[202:203]
	v_pk_fma_f32 v[204:205], v[116:117], v[116:117], v[204:205]
	v_pk_fma_f32 v[206:207], v[96:97], v[96:97], v[206:207]
	v_pk_fma_f32 v[208:209], v[108:109], v[108:109], v[208:209]
	v_pk_fma_f32 v[210:211], v[84:85], v[84:85], v[210:211]
	v_pk_fma_f32 v[212:213], v[76:77], v[76:77], v[212:213]
	v_pk_fma_f32 v[214:215], v[64:65], v[64:65], v[214:215]
	v_pk_fma_f32 v[200:201], v[134:135], v[134:135], v[200:201]
	v_pk_fma_f32 v[202:203], v[122:123], v[122:123], v[202:203]
	v_pk_fma_f32 v[204:205], v[118:119], v[118:119], v[204:205]
	v_pk_fma_f32 v[206:207], v[98:99], v[98:99], v[206:207]
	v_pk_fma_f32 v[208:209], v[110:111], v[110:111], v[208:209]
	v_pk_fma_f32 v[210:211], v[86:87], v[86:87], v[210:211]
	v_pk_fma_f32 v[212:213], v[78:79], v[78:79], v[212:213]
	v_pk_fma_f32 v[214:215], v[66:67], v[66:67], v[214:215]
	v_pk_fma_f32 v[200:201], v[56:57], v[56:57], v[200:201]
	v_pk_fma_f32 v[202:203], v[52:53], v[52:53], v[202:203]
	v_pk_fma_f32 v[204:205], v[40:41], v[40:41], v[204:205]
	v_pk_fma_f32 v[206:207], v[32:33], v[32:33], v[206:207]
	v_pk_fma_f32 v[208:209], v[36:37], v[36:37], v[208:209]
	v_pk_fma_f32 v[210:211], v[20:21], v[20:21], v[210:211]
	v_pk_fma_f32 v[212:213], v[12:13], v[12:13], v[212:213]
	v_pk_fma_f32 v[214:215], v[4:5], v[4:5], v[214:215]
	v_pk_fma_f32 v[200:201], v[58:59], v[58:59], v[200:201]
	v_pk_fma_f32 v[202:203], v[54:55], v[54:55], v[202:203]
	v_pk_fma_f32 v[204:205], v[42:43], v[42:43], v[204:205]
	v_pk_fma_f32 v[206:207], v[34:35], v[34:35], v[206:207]
	v_pk_fma_f32 v[208:209], v[38:39], v[38:39], v[208:209]
	v_pk_fma_f32 v[210:211], v[22:23], v[22:23], v[210:211]
	v_pk_fma_f32 v[212:213], v[14:15], v[14:15], v[212:213]
	v_pk_fma_f32 v[214:215], v[6:7], v[6:7], v[214:215]
	v_pk_fma_f32 v[200:201], v[60:61], v[60:61], v[200:201]
	v_pk_fma_f32 v[202:203], v[48:49], v[48:49], v[202:203]
	v_pk_fma_f32 v[204:205], v[44:45], v[44:45], v[204:205]
	v_pk_fma_f32 v[206:207], v[24:25], v[24:25], v[206:207]
	v_pk_fma_f32 v[208:209], v[28:29], v[28:29], v[208:209]
	v_pk_fma_f32 v[210:211], v[16:17], v[16:17], v[210:211]
	v_pk_fma_f32 v[212:213], v[8:9], v[8:9], v[212:213]
	v_pk_fma_f32 v[214:215], v[0:1], v[0:1], v[214:215]
	v_pk_fma_f32 v[200:201], v[62:63], v[62:63], v[200:201]
	v_pk_fma_f32 v[202:203], v[50:51], v[50:51], v[202:203]
	v_pk_fma_f32 v[204:205], v[46:47], v[46:47], v[204:205]
	v_pk_fma_f32 v[206:207], v[26:27], v[26:27], v[206:207]
	v_pk_fma_f32 v[208:209], v[30:31], v[30:31], v[208:209]
	v_pk_fma_f32 v[210:211], v[18:19], v[18:19], v[210:211]
	v_pk_fma_f32 v[212:213], v[10:11], v[10:11], v[212:213]
	v_pk_fma_f32 v[214:215], v[2:3], v[2:3], v[214:215]
	v_add_f32_e32 v216, v200, v201
	v_add_f32_e32 v217, v202, v203
	v_add_f32_e32 v218, v204, v205
	v_add_f32_e32 v219, v206, v207
	v_add_f32_e32 v220, v208, v209
	v_add_f32_e32 v221, v210, v211
	v_add_f32_e32 v222, v212, v213
	v_add_f32_e32 v223, v214, v215
	v_and_b32_e32 v224, 63, v154
	v_xor_b32_e32 v225, 32, v224
	v_xor_b32_e32 v224, 16, v224
	v_lshlrev_b32_e32 v224, 2, v224
	v_lshlrev_b32_e32 v225, 2, v225
	ds_bpermute_b32 v226, v224, v216
	ds_bpermute_b32 v227, v224, v217
	ds_bpermute_b32 v228, v224, v218
	ds_bpermute_b32 v229, v224, v219
	ds_bpermute_b32 v230, v224, v220
	ds_bpermute_b32 v231, v224, v221
	ds_bpermute_b32 v232, v224, v222
	ds_bpermute_b32 v233, v224, v223
	s_waitcnt lgkmcnt(0)
	v_add_f32_e32 v216, v216, v226
	v_add_f32_e32 v217, v217, v227
	v_add_f32_e32 v218, v218, v228
	v_add_f32_e32 v219, v219, v229
	v_add_f32_e32 v220, v220, v230
	v_add_f32_e32 v221, v221, v231
	v_add_f32_e32 v222, v222, v232
	v_add_f32_e32 v223, v223, v233
	ds_bpermute_b32 v226, v225, v216
	ds_bpermute_b32 v227, v225, v217
	ds_bpermute_b32 v228, v225, v218
	ds_bpermute_b32 v229, v225, v219
	ds_bpermute_b32 v230, v225, v220
	ds_bpermute_b32 v231, v225, v221
	ds_bpermute_b32 v232, v225, v222
	ds_bpermute_b32 v233, v225, v223
	s_waitcnt lgkmcnt(0)
	v_add_f32_e32 v216, v216, v226
	v_add_f32_e32 v217, v217, v227
	v_add_f32_e32 v218, v218, v228
	v_add_f32_e32 v219, v219, v229
	v_add_f32_e32 v220, v220, v230
	v_add_f32_e32 v221, v221, v231
	v_add_f32_e32 v222, v222, v232
	v_add_f32_e32 v223, v223, v233
	v_bfe_u32 v234, v154, 6, 2
	v_lshlrev_b32_e32 v234, 8, v234
	v_lshrrev_b32_e32 v235, 8, v154
	v_lshl_add_u32 v234, v235, 6, v234
	v_and_b32_e32 v235, 15, v154
	v_add_u32_e32 v234, v234, v235
	v_lshlrev_b32_e32 v234, 2, v234
	ds_write_b32 v234, v216 offset:0
	ds_write_b32 v234, v217 offset:64
	ds_write_b32 v234, v218 offset:128
	ds_write_b32 v234, v219 offset:192
	ds_write_b32 v234, v220 offset:512
	ds_write_b32 v234, v221 offset:576
	ds_write_b32 v234, v222 offset:640
	ds_write_b32 v234, v223 offset:704
	s_waitcnt lgkmcnt(0)
	s_barrier
	v_cmp_gt_u32_e32 vcc, 0x100, v154
	s_and_saveexec_b64 s[48:49], vcc
	v_lshlrev_b32_e32 v235, 2, v154
	ds_read_b32 v236, v235
	ds_read_b32 v237, v235 offset:1024
	ds_read_b32 v238, v235 offset:2048
	ds_read_b32 v239, v235 offset:3072
	s_lshl_b32 s50, s8, 3
	s_and_b32 s50, s50, 56
	s_bfe_u32 s51, s8, 0x30003
	s_or_b32 s50, s50, s51
	s_lshl_b32 s50, s50, 2
	s_lshr_b32 s51, s8, 6
	s_or_b32 s50, s50, s51
	s_lshl_b32 s50, s50, 10
	s_add_u32 s50, s50, s72
	s_addc_u32 s51, s73, 0
	s_add_u32 s50, s50, 0x8d00000
	s_addc_u32 s51, s51, 0
	s_waitcnt lgkmcnt(0)
	v_add_f32_e32 v236, v236, v237
	v_add_f32_e32 v238, v238, v239
	v_add_f32_e32 v236, v236, v238
	global_store_dword v235, v236, s[50:51]
	s_mov_b64 exec, s[48:49]
	s_mov_b32 s92, s8
	v_mov_b64_e32 v[242:243], v[0:1]
	v_mov_b64_e32 v[244:245], v[2:3]
	v_mov_b64_e32 v[246:247], v[4:5]
	v_mov_b64_e32 v[248:249], v[6:7]
	s_add_i32 s8, s8, s74
	s_add_i32 s13, s13, s20
	s_cmpk_lt_i32 s8, 0x100
	s_cbranch_scc0 .LBB0_594

.LBB0_624:
	s_or_b64 exec, exec, s[0:1]
	v_mov_b32_e32 v0, v154
	v_mov_b32_e32 v2, v154
	s_waitcnt lgkmcnt(0)
	s_barrier
	s_lshl_b32 s0, s92, 3
	s_and_b32 s0, s0, 56
	s_bfe_u32 s1, s92, 0x30003
	s_or_b32 s0, s0, s1
	s_lshr_b32 s1, s92, 6
	v_lshrrev_b32_e32 v140, 8, v154
	v_and_b32_e32 v141, 15, v154
	v_lshl_add_u32 v140, v140, 6, v141
	v_bfe_u32 v141, v154, 6, 2
	v_bfe_u32 v142, v154, 4, 2
	v_lshlrev_b32_e32 v141, 5, v141
	v_lshl_add_u32 v141, v142, 3, v141
	v_lshlrev_b32_e32 v142, 2, v140
	v_lshlrev_b32_e32 v143, 2, v141
	v_lshlrev_b32_e32 v144, 11, v140
	v_lshl_add_u32 v144, v141, 1, v144
	s_lshl_b32 s6, s0, 12
	s_add_u32 s6, s6, s72
	s_addc_u32 s7, s73, 0
	s_add_u32 s6, s6, 0x8d00000
	s_addc_u32 s7, s7, 0
	global_load_dword v170, v142, s[6:7] offset:0
	global_load_dword v171, v142, s[6:7] offset:1024
	global_load_dword v172, v142, s[6:7] offset:2048
	global_load_dword v173, v142, s[6:7] offset:3072
	global_load_dword v174, v142, s[6:7] offset:64
	global_load_dword v175, v142, s[6:7] offset:1088
	global_load_dword v176, v142, s[6:7] offset:2112
	global_load_dword v177, v142, s[6:7] offset:3136
	global_load_dword v178, v142, s[6:7] offset:128
	global_load_dword v179, v142, s[6:7] offset:1152
	global_load_dword v180, v142, s[6:7] offset:2176
	global_load_dword v181, v142, s[6:7] offset:3200
	global_load_dword v182, v142, s[6:7] offset:192
	global_load_dword v183, v142, s[6:7] offset:1216
	global_load_dword v184, v142, s[6:7] offset:2240
	global_load_dword v185, v142, s[6:7] offset:3264
	global_load_dword v186, v142, s[6:7] offset:512
	global_load_dword v187, v142, s[6:7] offset:1536
	global_load_dword v188, v142, s[6:7] offset:2560
	global_load_dword v189, v142, s[6:7] offset:3584
	global_load_dword v190, v142, s[6:7] offset:576
	global_load_dword v191, v142, s[6:7] offset:1600
	global_load_dword v192, v142, s[6:7] offset:2624
	global_load_dword v193, v142, s[6:7] offset:3648
	global_load_dword v194, v142, s[6:7] offset:640
	global_load_dword v195, v142, s[6:7] offset:1664
	global_load_dword v196, v142, s[6:7] offset:2688
	global_load_dword v197, v142, s[6:7] offset:3712
	global_load_dword v198, v142, s[6:7] offset:704
	global_load_dword v199, v142, s[6:7] offset:1728
	global_load_dword v200, v142, s[6:7] offset:2752
	global_load_dword v201, v142, s[6:7] offset:3776
	v_readlane_b32 s4, v254, 57
	s_lshl_b32 s4, s4, 12
	s_lshl_b32 s1, s1, 10
	v_readlane_b32 s8, v253, 5
	v_readlane_b32 s9, v253, 6
	s_add_u32 s8, s8, s4
	s_addc_u32 s9, s9, 0
	s_add_u32 s8, s8, s1
	s_addc_u32 s9, s9, 0
	s_lshr_b32 s4, s0, 3
	s_mul_i32 s4, s4, 0x9000
	s_add_u32 s4, s4, s1
	v_readlane_b32 s10, v254, 55
	v_readlane_b32 s11, v254, 56
	s_add_u32 s10, s10, s4
	s_addc_u32 s11, s11, 0
	s_add_u32 s12, s10, 0x6000
	s_addc_u32 s13, s11, 0
	s_add_u32 s10, s10, 0x7000
	s_addc_u32 s11, s11, 0
	global_load_dwordx4 v[204:207], v143, s[8:9]
	global_load_dwordx4 v[220:223], v143, s[10:11]
	global_load_dwordx4 v[236:239], v143, s[12:13]
	global_load_dwordx4 v[208:211], v143, s[8:9] offset:16
	global_load_dwordx4 v[224:227], v143, s[10:11] offset:16
	global_load_dwordx4 v[146:149], v143, s[12:13] offset:16
	global_load_dwordx4 v[212:215], v143, s[8:9] offset:512
	global_load_dwordx4 v[228:231], v143, s[10:11] offset:512
	global_load_dwordx4 v[150:153], v143, s[12:13] offset:512
	global_load_dwordx4 v[216:219], v143, s[8:9] offset:528
	global_load_dwordx4 v[232:235], v143, s[10:11] offset:528
	global_load_dwordx4 v[162:165], v143, s[12:13] offset:528
	v_readlane_b32 s14, v253, 47
	v_readlane_b32 s15, v253, 48
	s_lshl_b32 s4, s0, 19
	s_add_u32 s14, s14, s4
	s_addc_u32 s15, s15, 0
	s_lshr_b32 s4, s1, 1
	s_add_u32 s14, s14, s4
	s_addc_u32 s15, s15, 0
	s_waitcnt vmcnt(0)
	v_add_f32_e32 v170, v170, v171
	v_add_f32_e32 v172, v172, v173
	v_add_f32_e32 v174, v174, v175
	v_add_f32_e32 v176, v176, v177
	v_add_f32_e32 v178, v178, v179
	v_add_f32_e32 v180, v180, v181
	v_add_f32_e32 v182, v182, v183
	v_add_f32_e32 v184, v184, v185
	v_add_f32_e32 v186, v186, v187
	v_add_f32_e32 v188, v188, v189
	v_add_f32_e32 v190, v190, v191
	v_add_f32_e32 v192, v192, v193
	v_add_f32_e32 v194, v194, v195
	v_add_f32_e32 v196, v196, v197
	v_add_f32_e32 v198, v198, v199
	v_add_f32_e32 v200, v200, v201
	v_add_f32_e32 v170, v170, v172
	v_add_f32_e32 v174, v174, v176
	v_add_f32_e32 v178, v178, v180
	v_add_f32_e32 v182, v182, v184
	v_add_f32_e32 v186, v186, v188
	v_add_f32_e32 v190, v190, v192
	v_add_f32_e32 v194, v194, v196
	v_add_f32_e32 v198, v198, v200
	v_fmamk_f32 v170, v170, 0x3a800000, v155
	v_fmamk_f32 v174, v174, 0x3a800000, v155
	v_fmamk_f32 v178, v178, 0x3a800000, v155
	v_fmamk_f32 v182, v182, 0x3a800000, v155
	v_fmamk_f32 v186, v186, 0x3a800000, v155
	v_fmamk_f32 v190, v190, 0x3a800000, v155
	v_fmamk_f32 v194, v194, 0x3a800000, v155
	v_fmamk_f32 v198, v198, 0x3a800000, v155
	v_rsq_f32_e32 v170, v170
	v_rsq_f32_e32 v174, v174
	v_rsq_f32_e32 v178, v178
	v_rsq_f32_e32 v182, v182
	v_rsq_f32_e32 v186, v186
	v_rsq_f32_e32 v190, v190
	v_rsq_f32_e32 v194, v194
	v_rsq_f32_e32 v198, v198
	v_pk_add_f32 v[220:221], v[220:221], 1.0 op_sel_hi:[1,0]
	v_pk_add_f32 v[222:223], v[222:223], 1.0 op_sel_hi:[1,0]
	v_pk_add_f32 v[224:225], v[224:225], 1.0 op_sel_hi:[1,0]
	v_pk_add_f32 v[226:227], v[226:227], 1.0 op_sel_hi:[1,0]
	v_pk_add_f32 v[228:229], v[228:229], 1.0 op_sel_hi:[1,0]
	v_pk_add_f32 v[230:231], v[230:231], 1.0 op_sel_hi:[1,0]
	v_pk_add_f32 v[232:233], v[232:233], 1.0 op_sel_hi:[1,0]
	v_pk_add_f32 v[234:235], v[234:235], 1.0 op_sel_hi:[1,0]
	v_pk_mul_f32 v[128:129], v[128:129], v[170:171] op_sel_hi:[1,0]
	v_pk_mul_f32 v[130:131], v[130:131], v[170:171] op_sel_hi:[1,0]
	v_pk_mul_f32 v[132:133], v[132:133], v[170:171] op_sel_hi:[1,0]
	v_pk_mul_f32 v[134:135], v[134:135], v[170:171] op_sel_hi:[1,0]
	v_pk_mul_f32 v[128:129], v[204:205], v[128:129]
	v_pk_mul_f32 v[130:131], v[206:207], v[130:131]
	v_pk_mul_f32 v[132:133], v[208:209], v[132:133]
	v_pk_mul_f32 v[134:135], v[210:211], v[134:135]
	v_pk_fma_f32 v[128:129], v[220:221], v[128:129], v[236:237]
	v_pk_fma_f32 v[130:131], v[222:223], v[130:131], v[238:239]
	v_pk_fma_f32 v[132:133], v[224:225], v[132:133], v[146:147]
	v_pk_fma_f32 v[134:135], v[226:227], v[134:135], v[148:149]
	v_cvt_pk_bf16_f32 v128, v128, v129
	v_cvt_pk_bf16_f32 v129, v130, v131
	v_cvt_pk_bf16_f32 v130, v132, v133
	v_cvt_pk_bf16_f32 v131, v134, v135
	global_store_dwordx4 v144, v[128:131], s[14:15]
	v_pk_mul_f32 v[56:57], v[56:57], v[170:171] op_sel_hi:[1,0]
	v_pk_mul_f32 v[58:59], v[58:59], v[170:171] op_sel_hi:[1,0]
	v_pk_mul_f32 v[60:61], v[60:61], v[170:171] op_sel_hi:[1,0]
	v_pk_mul_f32 v[62:63], v[62:63], v[170:171] op_sel_hi:[1,0]
	v_pk_mul_f32 v[56:57], v[212:213], v[56:57]
	v_pk_mul_f32 v[58:59], v[214:215], v[58:59]
	v_pk_mul_f32 v[60:61], v[216:217], v[60:61]
	v_pk_mul_f32 v[62:63], v[218:219], v[62:63]
	v_pk_fma_f32 v[56:57], v[228:229], v[56:57], v[150:151]
	v_pk_fma_f32 v[58:59], v[230:231], v[58:59], v[152:153]
	v_pk_fma_f32 v[60:61], v[232:233], v[60:61], v[162:163]
	v_pk_fma_f32 v[62:63], v[234:235], v[62:63], v[164:165]
	v_cvt_pk_bf16_f32 v56, v56, v57
	v_cvt_pk_bf16_f32 v57, v58, v59
	v_cvt_pk_bf16_f32 v58, v60, v61
	v_cvt_pk_bf16_f32 v59, v62, v63
	global_store_dwordx4 v144, v[56:59], s[14:15] offset:256
	s_add_u32 s14, s14, 0x8000
	s_addc_u32 s15, s15, 0
	v_pk_mul_f32 v[124:125], v[124:125], v[174:175] op_sel_hi:[1,0]
	v_pk_mul_f32 v[126:127], v[126:127], v[174:175] op_sel_hi:[1,0]
	v_pk_mul_f32 v[120:121], v[120:121], v[174:175] op_sel_hi:[1,0]
	v_pk_mul_f32 v[122:123], v[122:123], v[174:175] op_sel_hi:[1,0]
	v_pk_mul_f32 v[124:125], v[204:205], v[124:125]
	v_pk_mul_f32 v[126:127], v[206:207], v[126:127]
	v_pk_mul_f32 v[120:121], v[208:209], v[120:121]
	v_pk_mul_f32 v[122:123], v[210:211], v[122:123]
	v_pk_fma_f32 v[124:125], v[220:221], v[124:125], v[236:237]
	v_pk_fma_f32 v[126:127], v[222:223], v[126:127], v[238:239]
	v_pk_fma_f32 v[120:121], v[224:225], v[120:121], v[146:147]
	v_pk_fma_f32 v[122:123], v[226:227], v[122:123], v[148:149]
	v_cvt_pk_bf16_f32 v124, v124, v125
	v_cvt_pk_bf16_f32 v125, v126, v127
	v_cvt_pk_bf16_f32 v126, v120, v121
	v_cvt_pk_bf16_f32 v127, v122, v123
	global_store_dwordx4 v144, v[124:127], s[14:15]
	v_pk_mul_f32 v[52:53], v[52:53], v[174:175] op_sel_hi:[1,0]
	v_pk_mul_f32 v[54:55], v[54:55], v[174:175] op_sel_hi:[1,0]
	v_pk_mul_f32 v[48:49], v[48:49], v[174:175] op_sel_hi:[1,0]
	v_pk_mul_f32 v[50:51], v[50:51], v[174:175] op_sel_hi:[1,0]
	v_pk_mul_f32 v[52:53], v[212:213], v[52:53]
	v_pk_mul_f32 v[54:55], v[214:215], v[54:55]
	v_pk_mul_f32 v[48:49], v[216:217], v[48:49]
	v_pk_mul_f32 v[50:51], v[218:219], v[50:51]
	v_pk_fma_f32 v[52:53], v[228:229], v[52:53], v[150:151]
	v_pk_fma_f32 v[54:55], v[230:231], v[54:55], v[152:153]
	v_pk_fma_f32 v[48:49], v[232:233], v[48:49], v[162:163]
	v_pk_fma_f32 v[50:51], v[234:235], v[50:51], v[164:165]
	v_cvt_pk_bf16_f32 v52, v52, v53
	v_cvt_pk_bf16_f32 v53, v54, v55
	v_cvt_pk_bf16_f32 v54, v48, v49
	v_cvt_pk_bf16_f32 v55, v50, v51
	global_store_dwordx4 v144, v[52:55], s[14:15] offset:256
	s_add_u32 s14, s14, 0x8000
	s_addc_u32 s15, s15, 0
	v_pk_mul_f32 v[112:113], v[112:113], v[178:179] op_sel_hi:[1,0]
	v_pk_mul_f32 v[114:115], v[114:115], v[178:179] op_sel_hi:[1,0]
	v_pk_mul_f32 v[116:117], v[116:117], v[178:179] op_sel_hi:[1,0]
	v_pk_mul_f32 v[118:119], v[118:119], v[178:179] op_sel_hi:[1,0]
	v_pk_mul_f32 v[112:113], v[204:205], v[112:113]
	v_pk_mul_f32 v[114:115], v[206:207], v[114:115]
	v_pk_mul_f32 v[116:117], v[208:209], v[116:117]
	v_pk_mul_f32 v[118:119], v[210:211], v[118:119]
	v_pk_fma_f32 v[112:113], v[220:221], v[112:113], v[236:237]
	v_pk_fma_f32 v[114:115], v[222:223], v[114:115], v[238:239]
	v_pk_fma_f32 v[116:117], v[224:225], v[116:117], v[146:147]
	v_pk_fma_f32 v[118:119], v[226:227], v[118:119], v[148:149]
	v_cvt_pk_bf16_f32 v112, v112, v113
	v_cvt_pk_bf16_f32 v113, v114, v115
	v_cvt_pk_bf16_f32 v114, v116, v117
	v_cvt_pk_bf16_f32 v115, v118, v119
	global_store_dwordx4 v144, v[112:115], s[14:15]
	v_pk_mul_f32 v[40:41], v[40:41], v[178:179] op_sel_hi:[1,0]
	v_pk_mul_f32 v[42:43], v[42:43], v[178:179] op_sel_hi:[1,0]
	v_pk_mul_f32 v[44:45], v[44:45], v[178:179] op_sel_hi:[1,0]
	v_pk_mul_f32 v[46:47], v[46:47], v[178:179] op_sel_hi:[1,0]
	v_pk_mul_f32 v[40:41], v[212:213], v[40:41]
	v_pk_mul_f32 v[42:43], v[214:215], v[42:43]
	v_pk_mul_f32 v[44:45], v[216:217], v[44:45]
	v_pk_mul_f32 v[46:47], v[218:219], v[46:47]
	v_pk_fma_f32 v[40:41], v[228:229], v[40:41], v[150:151]
	v_pk_fma_f32 v[42:43], v[230:231], v[42:43], v[152:153]
	v_pk_fma_f32 v[44:45], v[232:233], v[44:45], v[162:163]
	v_pk_fma_f32 v[46:47], v[234:235], v[46:47], v[164:165]
	v_cvt_pk_bf16_f32 v40, v40, v41
	v_cvt_pk_bf16_f32 v41, v42, v43
	v_cvt_pk_bf16_f32 v42, v44, v45
	v_cvt_pk_bf16_f32 v43, v46, v47
	global_store_dwordx4 v144, v[40:43], s[14:15] offset:256
	s_add_u32 s14, s14, 0x8000
	s_addc_u32 s15, s15, 0
	v_pk_mul_f32 v[100:101], v[100:101], v[182:183] op_sel_hi:[1,0]
	v_pk_mul_f32 v[102:103], v[102:103], v[182:183] op_sel_hi:[1,0]
	v_pk_mul_f32 v[96:97], v[96:97], v[182:183] op_sel_hi:[1,0]
	v_pk_mul_f32 v[98:99], v[98:99], v[182:183] op_sel_hi:[1,0]
	v_pk_mul_f32 v[100:101], v[204:205], v[100:101]
	v_pk_mul_f32 v[102:103], v[206:207], v[102:103]
	v_pk_mul_f32 v[96:97], v[208:209], v[96:97]
	v_pk_mul_f32 v[98:99], v[210:211], v[98:99]
	v_pk_fma_f32 v[100:101], v[220:221], v[100:101], v[236:237]
	v_pk_fma_f32 v[102:103], v[222:223], v[102:103], v[238:239]
	v_pk_fma_f32 v[96:97], v[224:225], v[96:97], v[146:147]
	v_pk_fma_f32 v[98:99], v[226:227], v[98:99], v[148:149]
	v_cvt_pk_bf16_f32 v100, v100, v101
	v_cvt_pk_bf16_f32 v101, v102, v103
	v_cvt_pk_bf16_f32 v102, v96, v97
	v_cvt_pk_bf16_f32 v103, v98, v99
	global_store_dwordx4 v144, v[100:103], s[14:15]
	v_pk_mul_f32 v[32:33], v[32:33], v[182:183] op_sel_hi:[1,0]
	v_pk_mul_f32 v[34:35], v[34:35], v[182:183] op_sel_hi:[1,0]
	v_pk_mul_f32 v[24:25], v[24:25], v[182:183] op_sel_hi:[1,0]
	v_pk_mul_f32 v[26:27], v[26:27], v[182:183] op_sel_hi:[1,0]
	v_pk_mul_f32 v[32:33], v[212:213], v[32:33]
	v_pk_mul_f32 v[34:35], v[214:215], v[34:35]
	v_pk_mul_f32 v[24:25], v[216:217], v[24:25]
	v_pk_mul_f32 v[26:27], v[218:219], v[26:27]
	v_pk_fma_f32 v[32:33], v[228:229], v[32:33], v[150:151]
	v_pk_fma_f32 v[34:35], v[230:231], v[34:35], v[152:153]
	v_pk_fma_f32 v[24:25], v[232:233], v[24:25], v[162:163]
	v_pk_fma_f32 v[26:27], v[234:235], v[26:27], v[164:165]
	v_cvt_pk_bf16_f32 v32, v32, v33
	v_cvt_pk_bf16_f32 v33, v34, v35
	v_cvt_pk_bf16_f32 v34, v24, v25
	v_cvt_pk_bf16_f32 v35, v26, v27
	global_store_dwordx4 v144, v[32:35], s[14:15] offset:256
	s_add_u32 s14, s14, 0x28000
	s_addc_u32 s15, s15, 0
	v_pk_mul_f32 v[104:105], v[104:105], v[186:187] op_sel_hi:[1,0]
	v_pk_mul_f32 v[106:107], v[106:107], v[186:187] op_sel_hi:[1,0]
	v_pk_mul_f32 v[108:109], v[108:109], v[186:187] op_sel_hi:[1,0]
	v_pk_mul_f32 v[110:111], v[110:111], v[186:187] op_sel_hi:[1,0]
	v_pk_mul_f32 v[104:105], v[204:205], v[104:105]
	v_pk_mul_f32 v[106:107], v[206:207], v[106:107]
	v_pk_mul_f32 v[108:109], v[208:209], v[108:109]
	v_pk_mul_f32 v[110:111], v[210:211], v[110:111]
	v_pk_fma_f32 v[104:105], v[220:221], v[104:105], v[236:237]
	v_pk_fma_f32 v[106:107], v[222:223], v[106:107], v[238:239]
	v_pk_fma_f32 v[108:109], v[224:225], v[108:109], v[146:147]
	v_pk_fma_f32 v[110:111], v[226:227], v[110:111], v[148:149]
	v_cvt_pk_bf16_f32 v104, v104, v105
	v_cvt_pk_bf16_f32 v105, v106, v107
	v_cvt_pk_bf16_f32 v106, v108, v109
	v_cvt_pk_bf16_f32 v107, v110, v111
	global_store_dwordx4 v144, v[104:107], s[14:15]
	v_pk_mul_f32 v[36:37], v[36:37], v[186:187] op_sel_hi:[1,0]
	v_pk_mul_f32 v[38:39], v[38:39], v[186:187] op_sel_hi:[1,0]
	v_pk_mul_f32 v[28:29], v[28:29], v[186:187] op_sel_hi:[1,0]
	v_pk_mul_f32 v[30:31], v[30:31], v[186:187] op_sel_hi:[1,0]
	v_pk_mul_f32 v[36:37], v[212:213], v[36:37]
	v_pk_mul_f32 v[38:39], v[214:215], v[38:39]
	v_pk_mul_f32 v[28:29], v[216:217], v[28:29]
	v_pk_mul_f32 v[30:31], v[218:219], v[30:31]
	v_pk_fma_f32 v[36:37], v[228:229], v[36:37], v[150:151]
	v_pk_fma_f32 v[38:39], v[230:231], v[38:39], v[152:153]
	v_pk_fma_f32 v[28:29], v[232:233], v[28:29], v[162:163]
	v_pk_fma_f32 v[30:31], v[234:235], v[30:31], v[164:165]
	v_cvt_pk_bf16_f32 v36, v36, v37
	v_cvt_pk_bf16_f32 v37, v38, v39
	v_cvt_pk_bf16_f32 v38, v28, v29
	v_cvt_pk_bf16_f32 v39, v30, v31
	global_store_dwordx4 v144, v[36:39], s[14:15] offset:256
	s_add_u32 s14, s14, 0x8000
	s_addc_u32 s15, s15, 0
	v_pk_mul_f32 v[92:93], v[92:93], v[190:191] op_sel_hi:[1,0]
	v_pk_mul_f32 v[94:95], v[94:95], v[190:191] op_sel_hi:[1,0]
	v_pk_mul_f32 v[84:85], v[84:85], v[190:191] op_sel_hi:[1,0]
	v_pk_mul_f32 v[86:87], v[86:87], v[190:191] op_sel_hi:[1,0]
	v_pk_mul_f32 v[92:93], v[204:205], v[92:93]
	v_pk_mul_f32 v[94:95], v[206:207], v[94:95]
	v_pk_mul_f32 v[84:85], v[208:209], v[84:85]
	v_pk_mul_f32 v[86:87], v[210:211], v[86:87]
	v_pk_fma_f32 v[92:93], v[220:221], v[92:93], v[236:237]
	v_pk_fma_f32 v[94:95], v[222:223], v[94:95], v[238:239]
	v_pk_fma_f32 v[84:85], v[224:225], v[84:85], v[146:147]
	v_pk_fma_f32 v[86:87], v[226:227], v[86:87], v[148:149]
	v_cvt_pk_bf16_f32 v92, v92, v93
	v_cvt_pk_bf16_f32 v93, v94, v95
	v_cvt_pk_bf16_f32 v94, v84, v85
	v_cvt_pk_bf16_f32 v95, v86, v87
	global_store_dwordx4 v144, v[92:95], s[14:15]
	v_pk_mul_f32 v[20:21], v[20:21], v[190:191] op_sel_hi:[1,0]
	v_pk_mul_f32 v[22:23], v[22:23], v[190:191] op_sel_hi:[1,0]
	v_pk_mul_f32 v[16:17], v[16:17], v[190:191] op_sel_hi:[1,0]
	v_pk_mul_f32 v[18:19], v[18:19], v[190:191] op_sel_hi:[1,0]
	v_pk_mul_f32 v[20:21], v[212:213], v[20:21]
	v_pk_mul_f32 v[22:23], v[214:215], v[22:23]
	v_pk_mul_f32 v[16:17], v[216:217], v[16:17]
	v_pk_mul_f32 v[18:19], v[218:219], v[18:19]
	v_pk_fma_f32 v[20:21], v[228:229], v[20:21], v[150:151]
	v_pk_fma_f32 v[22:23], v[230:231], v[22:23], v[152:153]
	v_pk_fma_f32 v[16:17], v[232:233], v[16:17], v[162:163]
	v_pk_fma_f32 v[18:19], v[234:235], v[18:19], v[164:165]
	v_cvt_pk_bf16_f32 v20, v20, v21
	v_cvt_pk_bf16_f32 v21, v22, v23
	v_cvt_pk_bf16_f32 v22, v16, v17
	v_cvt_pk_bf16_f32 v23, v18, v19
	global_store_dwordx4 v144, v[20:23], s[14:15] offset:256
	s_add_u32 s14, s14, 0x8000
	s_addc_u32 s15, s15, 0
	v_pk_mul_f32 v[72:73], v[72:73], v[194:195] op_sel_hi:[1,0]
	v_pk_mul_f32 v[74:75], v[74:75], v[194:195] op_sel_hi:[1,0]
	v_pk_mul_f32 v[76:77], v[76:77], v[194:195] op_sel_hi:[1,0]
	v_pk_mul_f32 v[78:79], v[78:79], v[194:195] op_sel_hi:[1,0]
	v_pk_mul_f32 v[72:73], v[204:205], v[72:73]
	v_pk_mul_f32 v[74:75], v[206:207], v[74:75]
	v_pk_mul_f32 v[76:77], v[208:209], v[76:77]
	v_pk_mul_f32 v[78:79], v[210:211], v[78:79]
	v_pk_fma_f32 v[72:73], v[220:221], v[72:73], v[236:237]
	v_pk_fma_f32 v[74:75], v[222:223], v[74:75], v[238:239]
	v_pk_fma_f32 v[76:77], v[224:225], v[76:77], v[146:147]
	v_pk_fma_f32 v[78:79], v[226:227], v[78:79], v[148:149]
	v_cvt_pk_bf16_f32 v72, v72, v73
	v_cvt_pk_bf16_f32 v73, v74, v75
	v_cvt_pk_bf16_f32 v74, v76, v77
	v_cvt_pk_bf16_f32 v75, v78, v79
	global_store_dwordx4 v144, v[72:75], s[14:15]
	v_pk_mul_f32 v[12:13], v[12:13], v[194:195] op_sel_hi:[1,0]
	v_pk_mul_f32 v[14:15], v[14:15], v[194:195] op_sel_hi:[1,0]
	v_pk_mul_f32 v[8:9], v[8:9], v[194:195] op_sel_hi:[1,0]
	v_pk_mul_f32 v[10:11], v[10:11], v[194:195] op_sel_hi:[1,0]
	v_pk_mul_f32 v[12:13], v[212:213], v[12:13]
	v_pk_mul_f32 v[14:15], v[214:215], v[14:15]
	v_pk_mul_f32 v[8:9], v[216:217], v[8:9]
	v_pk_mul_f32 v[10:11], v[218:219], v[10:11]
	v_pk_fma_f32 v[12:13], v[228:229], v[12:13], v[150:151]
	v_pk_fma_f32 v[14:15], v[230:231], v[14:15], v[152:153]
	v_pk_fma_f32 v[8:9], v[232:233], v[8:9], v[162:163]
	v_pk_fma_f32 v[10:11], v[234:235], v[10:11], v[164:165]
	v_cvt_pk_bf16_f32 v12, v12, v13
	v_cvt_pk_bf16_f32 v13, v14, v15
	v_cvt_pk_bf16_f32 v14, v8, v9
	v_cvt_pk_bf16_f32 v15, v10, v11
	global_store_dwordx4 v144, v[12:15], s[14:15] offset:256
	s_add_u32 s14, s14, 0x8000
	s_addc_u32 s15, s15, 0
	v_pk_mul_f32 v[68:69], v[68:69], v[198:199] op_sel_hi:[1,0]
	v_pk_mul_f32 v[70:71], v[70:71], v[198:199] op_sel_hi:[1,0]
	v_pk_mul_f32 v[64:65], v[64:65], v[198:199] op_sel_hi:[1,0]
	v_pk_mul_f32 v[66:67], v[66:67], v[198:199] op_sel_hi:[1,0]
	v_pk_mul_f32 v[68:69], v[204:205], v[68:69]
	v_pk_mul_f32 v[70:71], v[206:207], v[70:71]
	v_pk_mul_f32 v[64:65], v[208:209], v[64:65]
	v_pk_mul_f32 v[66:67], v[210:211], v[66:67]
	v_pk_fma_f32 v[68:69], v[220:221], v[68:69], v[236:237]
	v_pk_fma_f32 v[70:71], v[222:223], v[70:71], v[238:239]
	v_pk_fma_f32 v[64:65], v[224:225], v[64:65], v[146:147]
	v_pk_fma_f32 v[66:67], v[226:227], v[66:67], v[148:149]
	v_cvt_pk_bf16_f32 v68, v68, v69
	v_cvt_pk_bf16_f32 v69, v70, v71
	v_cvt_pk_bf16_f32 v70, v64, v65
	v_cvt_pk_bf16_f32 v71, v66, v67
	global_store_dwordx4 v144, v[68:71], s[14:15]
	v_pk_mul_f32 v[246:247], v[246:247], v[198:199] op_sel_hi:[1,0]
	v_pk_mul_f32 v[248:249], v[248:249], v[198:199] op_sel_hi:[1,0]
	v_pk_mul_f32 v[242:243], v[242:243], v[198:199] op_sel_hi:[1,0]
	v_pk_mul_f32 v[244:245], v[244:245], v[198:199] op_sel_hi:[1,0]
	v_pk_mul_f32 v[246:247], v[212:213], v[246:247]
	v_pk_mul_f32 v[248:249], v[214:215], v[248:249]
	v_pk_mul_f32 v[242:243], v[216:217], v[242:243]
	v_pk_mul_f32 v[244:245], v[218:219], v[244:245]
	v_pk_fma_f32 v[246:247], v[228:229], v[246:247], v[150:151]
	v_pk_fma_f32 v[248:249], v[230:231], v[248:249], v[152:153]
	v_pk_fma_f32 v[242:243], v[232:233], v[242:243], v[162:163]
	v_pk_fma_f32 v[244:245], v[234:235], v[244:245], v[164:165]
	v_cvt_pk_bf16_f32 v246, v246, v247
	v_cvt_pk_bf16_f32 v247, v248, v249
	v_cvt_pk_bf16_f32 v248, v242, v243
	v_cvt_pk_bf16_f32 v249, v244, v245
	global_store_dwordx4 v144, v[246:249], s[14:15] offset:256
	s_branch .LBB0_627
	v_readlane_b32 s0, v253, 0
	v_readfirstlane_b32 s1, v2
	s_ashr_i32 s1, s1, 6
	s_lshl_b32 s0, s0, 3
	s_and_b32 s1, s1, -4
	v_lshrrev_b32_e32 v1, 6, v0
	s_add_i32 s1, s1, s0
	v_and_or_b32 v16, v1, 3, s1
	s_movk_i32 s0, 0x4000
	v_cmp_gt_i32_e32 vcc, s0, v16
	s_and_saveexec_b64 s[0:1], vcc
	v_readlane_b32 s26, v254, 47
	v_readlane_b32 s36, v254, 49
	s_movk_i32 s6, 0x3fff
	v_readlane_b32 s27, v254, 48
	v_readlane_b32 s37, v254, 50
	s_cbranch_execz .LBB0_627
	v_readlane_b32 s4, v254, 58
	v_readlane_b32 s5, v254, 59
	v_readlane_b32 s8, v253, 1
	s_lshl_b64 s[4:5], s[4:5], 2
	v_readlane_b32 s12, v253, 5
	v_readlane_b32 s13, v253, 6
	s_add_u32 s4, s12, s4
	v_and_b32_e32 v2, 63, v0
	s_addc_u32 s5, s13, s5
	v_lshlrev_b32_e32 v136, 5, v2
	v_lshl_add_u64 v[18:19], s[4:5], 0, v[136:137]
	v_readlane_b32 s4, v254, 55
	v_lshlrev_b32_e32 v0, 2, v2
	v_readlane_b32 s5, v254, 56
	v_xor_b32_e32 v29, 64, v0
	v_xor_b32_e32 v34, 0x80, v0
	v_lshl_add_u64 v[0:1], s[4:5], 0, v[136:137]
	s_mov_b64 s[4:5], 0x7000
	v_lshl_add_u64 v[20:21], v[0:1], 0, s[4:5]
	s_mov_b64 s[4:5], 0x6000
	v_ashrrev_i32_e32 v17, 31, v16
	v_lshl_add_u64 v[22:23], v[0:1], 0, s[4:5]
	v_lshlrev_b64 v[0:1], 11, v[16:17]
	v_readlane_b32 s4, v253, 47
	v_lshl_or_b32 v0, v2, 4, v0
	v_readlane_b32 s5, v253, 48
	v_readlane_b32 s9, v253, 2
	v_readlane_b32 s10, v253, 3
	v_lshl_add_u64 v[24:25], s[4:5], 0, v[0:1]
	v_lshlrev_b64 v[0:1], 12, v[16:17]
	v_or_b32_e32 v0, v0, v136
	v_lshl_add_u64 v[26:27], s[70:71], 0, v[0:1]
	s_mov_b64 s[4:5], 0
	v_readlane_b32 s11, v253, 4
	v_readlane_b32 s14, v253, 7
	v_readlane_b32 s15, v253, 8

.LBB0_698:
	s_or_b64 exec, exec, s[0:1]
	v_mov_b32_e32 v80, v154
	s_lshr_b32 s1, s10, 3
	v_and_b32_e32 v136, 15, v80
	v_lshrrev_b32_e32 v81, 1, v80
	v_ashrrev_i32_e32 v80, 2, v80
	s_lshl_b32 s0, s12, 8
	s_mul_i32 s1, s1, 0x9000
	v_and_b32_e32 v152, 0xffffffc0, v80
	v_and_b32_e32 v81, 0x78, v81
	s_add_u32 s10, s7, s1
	v_ashrrev_i32_e32 v153, 31, v152
	s_mov_b32 s1, s52
	v_lshl_or_b32 v144, s11, 8, v81
	v_lshl_add_u64 v[140:141], v[152:153], 0, s[0:1]
	v_ashrrev_i32_e32 v145, 31, v144
	v_or_b32_e32 v140, v140, v136
	s_addc_u32 s11, s8, 0
	v_lshlrev_b64 v[150:151], 2, v[144:145]
	v_lshlrev_b64 v[140:141], 12, v[140:141]
	v_lshl_add_u64 v[148:149], s[10:11], 0, v[150:151]
	v_lshl_add_u64 v[170:171], s[70:71], 0, v[140:141]
	v_lshl_add_u64 v[146:147], v[170:171], 0, v[150:151]
	s_nop 1
	v_readfirstlane_b32 s38, v146
	v_readfirstlane_b32 s39, v147
	s_nop 1
	v_subrev_u32_e32 v139, s38, v146
	s_mov_b64 s[40:41], s[38:39]
	s_mov_b64 s[42:43], s[38:39]
	s_mov_b64 s[44:45], s[40:41]
	s_mov_b64 s[46:47], s[42:43]
	global_load_dwordx4 v[234:237], v[148:149], off
	global_load_dwordx4 v[238:241], v[148:149], off offset:16
	global_load_dwordx4 v[242:245], v[148:149], off offset:512
	global_load_dwordx4 v[246:249], v[148:149], off offset:528
	global_load_dwordx4 v[178:181], v139, s[40:41]
	global_load_dwordx4 v[182:185], v139, s[40:41] offset:16
	s_add_u32 s40, s40, 0x10000
	s_addc_u32 s41, s41, 0
	global_load_dwordx4 v[186:189], v139, s[40:41]
	global_load_dwordx4 v[190:193], v139, s[40:41] offset:16
	s_add_u32 s40, s40, 0x10000
	s_addc_u32 s41, s41, 0
	global_load_dwordx4 v[194:197], v139, s[40:41]
	global_load_dwordx4 v[198:201], v139, s[40:41] offset:16
	s_add_u32 s40, s40, 0x10000
	s_addc_u32 s41, s41, 0
	global_load_dwordx4 v[202:205], v139, s[40:41]
	global_load_dwordx4 v[206:209], v139, s[40:41] offset:16
	s_add_u32 s40, s40, 0x50000
	s_addc_u32 s41, s41, 0
	global_load_dwordx4 v[210:213], v139, s[40:41]
	global_load_dwordx4 v[214:217], v139, s[40:41] offset:16
	s_add_u32 s40, s40, 0x10000
	s_addc_u32 s41, s41, 0
	global_load_dwordx4 v[218:221], v139, s[40:41]
	global_load_dwordx4 v[222:225], v139, s[40:41] offset:16
	s_add_u32 s40, s40, 0x10000
	s_addc_u32 s41, s41, 0
	global_load_dwordx4 v[226:229], v139, s[40:41]
	global_load_dwordx4 v[230:233], v139, s[40:41] offset:16
	s_add_u32 s40, s40, 0x10000
	s_addc_u32 s41, s41, 0
	s_waitcnt vmcnt(12)
	v_pk_mul_f32 v[132:133], v[132:133], v[234:235]
	v_pk_mul_f32 v[134:135], v[134:135], v[236:237]
	v_pk_mul_f32 v[128:129], v[128:129], v[238:239]
	v_pk_mul_f32 v[130:131], v[130:131], v[240:241]
	v_pk_fma_f32 v[132:133], v[132:133], 0.5, v[178:179] op_sel_hi:[1,0,1]
	v_pk_fma_f32 v[134:135], v[134:135], 0.5, v[180:181] op_sel_hi:[1,0,1]
	v_pk_fma_f32 v[128:129], v[128:129], 0.5, v[182:183] op_sel_hi:[1,0,1]
	v_pk_fma_f32 v[130:131], v[130:131], 0.5, v[184:185] op_sel_hi:[1,0,1]
	global_store_dwordx4 v139, v[132:135], s[42:43]
	global_store_dwordx4 v139, v[128:131], s[42:43] offset:16
	s_add_u32 s42, s42, 0x10000
	s_addc_u32 s43, s43, 0
	global_load_dwordx4 v[178:181], v139, s[40:41]
	global_load_dwordx4 v[182:185], v139, s[40:41] offset:16
	s_mov_b64 s[40:41], s[44:45]
	s_waitcnt vmcnt(14)
	v_pk_mul_f32 v[124:125], v[124:125], v[234:235]
	v_pk_mul_f32 v[126:127], v[126:127], v[236:237]
	v_pk_mul_f32 v[120:121], v[120:121], v[238:239]
	v_pk_mul_f32 v[122:123], v[122:123], v[240:241]
	v_pk_fma_f32 v[124:125], v[124:125], 0.5, v[186:187] op_sel_hi:[1,0,1]
	v_pk_fma_f32 v[126:127], v[126:127], 0.5, v[188:189] op_sel_hi:[1,0,1]
	v_pk_fma_f32 v[120:121], v[120:121], 0.5, v[190:191] op_sel_hi:[1,0,1]
	v_pk_fma_f32 v[122:123], v[122:123], 0.5, v[192:193] op_sel_hi:[1,0,1]
	global_store_dwordx4 v139, v[124:127], s[42:43]
	global_store_dwordx4 v139, v[120:123], s[42:43] offset:16
	s_add_u32 s42, s42, 0x10000
	s_addc_u32 s43, s43, 0
	global_load_dwordx4 v[186:189], v139, s[40:41] offset:512
	global_load_dwordx4 v[190:193], v139, s[40:41] offset:528
	s_add_u32 s40, s40, 0x10000
	s_addc_u32 s41, s41, 0
	s_waitcnt vmcnt(16)
	v_pk_mul_f32 v[116:117], v[116:117], v[234:235]
	v_pk_mul_f32 v[118:119], v[118:119], v[236:237]
	v_pk_mul_f32 v[112:113], v[112:113], v[238:239]
	v_pk_mul_f32 v[114:115], v[114:115], v[240:241]
	v_pk_fma_f32 v[116:117], v[116:117], 0.5, v[194:195] op_sel_hi:[1,0,1]
	v_pk_fma_f32 v[118:119], v[118:119], 0.5, v[196:197] op_sel_hi:[1,0,1]
	v_pk_fma_f32 v[112:113], v[112:113], 0.5, v[198:199] op_sel_hi:[1,0,1]
	v_pk_fma_f32 v[114:115], v[114:115], 0.5, v[200:201] op_sel_hi:[1,0,1]
	global_store_dwordx4 v139, v[116:119], s[42:43]
	global_store_dwordx4 v139, v[112:115], s[42:43] offset:16
	s_add_u32 s42, s42, 0x10000
	s_addc_u32 s43, s43, 0
	global_load_dwordx4 v[194:197], v139, s[40:41] offset:512
	global_load_dwordx4 v[198:201], v139, s[40:41] offset:528
	s_add_u32 s40, s40, 0x10000
	s_addc_u32 s41, s41, 0
	s_waitcnt vmcnt(18)
	v_pk_mul_f32 v[108:109], v[108:109], v[234:235]
	v_pk_mul_f32 v[110:111], v[110:111], v[236:237]
	v_pk_mul_f32 v[104:105], v[104:105], v[238:239]
	v_pk_mul_f32 v[106:107], v[106:107], v[240:241]
	v_pk_fma_f32 v[108:109], v[108:109], 0.5, v[202:203] op_sel_hi:[1,0,1]
	v_pk_fma_f32 v[110:111], v[110:111], 0.5, v[204:205] op_sel_hi:[1,0,1]
	v_pk_fma_f32 v[104:105], v[104:105], 0.5, v[206:207] op_sel_hi:[1,0,1]
	v_pk_fma_f32 v[106:107], v[106:107], 0.5, v[208:209] op_sel_hi:[1,0,1]
	global_store_dwordx4 v139, v[108:111], s[42:43]
	global_store_dwordx4 v139, v[104:107], s[42:43] offset:16
	s_add_u32 s42, s42, 0x50000
	s_addc_u32 s43, s43, 0
	global_load_dwordx4 v[202:205], v139, s[40:41] offset:512
	global_load_dwordx4 v[206:209], v139, s[40:41] offset:528
	s_add_u32 s40, s40, 0x10000
	s_addc_u32 s41, s41, 0
	s_waitcnt vmcnt(20)
	v_pk_mul_f32 v[100:101], v[100:101], v[234:235]
	v_pk_mul_f32 v[102:103], v[102:103], v[236:237]
	v_pk_mul_f32 v[96:97], v[96:97], v[238:239]
	v_pk_mul_f32 v[98:99], v[98:99], v[240:241]
	v_pk_fma_f32 v[100:101], v[100:101], 0.5, v[210:211] op_sel_hi:[1,0,1]
	v_pk_fma_f32 v[102:103], v[102:103], 0.5, v[212:213] op_sel_hi:[1,0,1]
	v_pk_fma_f32 v[96:97], v[96:97], 0.5, v[214:215] op_sel_hi:[1,0,1]
	v_pk_fma_f32 v[98:99], v[98:99], 0.5, v[216:217] op_sel_hi:[1,0,1]
	global_store_dwordx4 v139, v[100:103], s[42:43]
	global_store_dwordx4 v139, v[96:99], s[42:43] offset:16
	s_add_u32 s42, s42, 0x10000
	s_addc_u32 s43, s43, 0
	global_load_dwordx4 v[210:213], v139, s[40:41] offset:512
	global_load_dwordx4 v[214:217], v139, s[40:41] offset:528
	s_add_u32 s40, s40, 0x50000
	s_addc_u32 s41, s41, 0
	s_waitcnt vmcnt(22)
	v_pk_mul_f32 v[92:93], v[92:93], v[234:235]
	v_pk_mul_f32 v[94:95], v[94:95], v[236:237]
	v_pk_mul_f32 v[88:89], v[88:89], v[238:239]
	v_pk_mul_f32 v[90:91], v[90:91], v[240:241]
	v_pk_fma_f32 v[92:93], v[92:93], 0.5, v[218:219] op_sel_hi:[1,0,1]
	v_pk_fma_f32 v[94:95], v[94:95], 0.5, v[220:221] op_sel_hi:[1,0,1]
	v_pk_fma_f32 v[88:89], v[88:89], 0.5, v[222:223] op_sel_hi:[1,0,1]
	v_pk_fma_f32 v[90:91], v[90:91], 0.5, v[224:225] op_sel_hi:[1,0,1]
	global_store_dwordx4 v139, v[92:95], s[42:43]
	global_store_dwordx4 v139, v[88:91], s[42:43] offset:16
	s_add_u32 s42, s42, 0x10000
	s_addc_u32 s43, s43, 0
	global_load_dwordx4 v[218:221], v139, s[40:41] offset:512
	global_load_dwordx4 v[222:225], v139, s[40:41] offset:528
	s_add_u32 s40, s40, 0x10000
	s_addc_u32 s41, s41, 0
	s_waitcnt vmcnt(24)
	v_pk_mul_f32 v[76:77], v[76:77], v[234:235]
	v_pk_mul_f32 v[78:79], v[78:79], v[236:237]
	v_pk_mul_f32 v[72:73], v[72:73], v[238:239]
	v_pk_mul_f32 v[74:75], v[74:75], v[240:241]
	v_pk_fma_f32 v[76:77], v[76:77], 0.5, v[226:227] op_sel_hi:[1,0,1]
	v_pk_fma_f32 v[78:79], v[78:79], 0.5, v[228:229] op_sel_hi:[1,0,1]
	v_pk_fma_f32 v[72:73], v[72:73], 0.5, v[230:231] op_sel_hi:[1,0,1]
	v_pk_fma_f32 v[74:75], v[74:75], 0.5, v[232:233] op_sel_hi:[1,0,1]
	global_store_dwordx4 v139, v[76:79], s[42:43]
	global_store_dwordx4 v139, v[72:75], s[42:43] offset:16
	s_add_u32 s42, s42, 0x10000
	s_addc_u32 s43, s43, 0
	global_load_dwordx4 v[226:229], v139, s[40:41] offset:512
	global_load_dwordx4 v[230:233], v139, s[40:41] offset:528
	s_add_u32 s40, s40, 0x10000
	s_addc_u32 s41, s41, 0
	s_waitcnt vmcnt(24)
	v_pk_mul_f32 v[68:69], v[68:69], v[234:235]
	v_pk_mul_f32 v[70:71], v[70:71], v[236:237]
	v_pk_mul_f32 v[64:65], v[64:65], v[238:239]
	v_pk_mul_f32 v[66:67], v[66:67], v[240:241]
	v_pk_fma_f32 v[68:69], v[68:69], 0.5, v[178:179] op_sel_hi:[1,0,1]
	v_pk_fma_f32 v[70:71], v[70:71], 0.5, v[180:181] op_sel_hi:[1,0,1]
	v_pk_fma_f32 v[64:65], v[64:65], 0.5, v[182:183] op_sel_hi:[1,0,1]
	v_pk_fma_f32 v[66:67], v[66:67], 0.5, v[184:185] op_sel_hi:[1,0,1]
	global_store_dwordx4 v139, v[68:71], s[42:43]
	global_store_dwordx4 v139, v[64:67], s[42:43] offset:16
	s_mov_b64 s[42:43], s[46:47]
	global_load_dwordx4 v[178:181], v139, s[40:41] offset:512
	global_load_dwordx4 v[182:185], v139, s[40:41] offset:528
	s_add_u32 s40, s40, 0x10000
	s_addc_u32 s41, s41, 0
	s_waitcnt vmcnt(24)
	v_pk_mul_f32 v[60:61], v[60:61], v[242:243]
	v_pk_mul_f32 v[62:63], v[62:63], v[244:245]
	v_pk_mul_f32 v[56:57], v[56:57], v[246:247]
	v_pk_mul_f32 v[58:59], v[58:59], v[248:249]
	v_pk_fma_f32 v[60:61], v[60:61], 0.5, v[186:187] op_sel_hi:[1,0,1]
	v_pk_fma_f32 v[62:63], v[62:63], 0.5, v[188:189] op_sel_hi:[1,0,1]
	v_pk_fma_f32 v[56:57], v[56:57], 0.5, v[190:191] op_sel_hi:[1,0,1]
	v_pk_fma_f32 v[58:59], v[58:59], 0.5, v[192:193] op_sel_hi:[1,0,1]
	global_store_dwordx4 v139, v[60:63], s[42:43] offset:512
	global_store_dwordx4 v139, v[56:59], s[42:43] offset:528
	s_add_u32 s42, s42, 0x10000
	s_addc_u32 s43, s43, 0
	global_load_dwordx4 v[186:189], v139, s[40:41] offset:512
	global_load_dwordx4 v[190:193], v139, s[40:41] offset:528
	s_waitcnt vmcnt(24)
	v_pk_mul_f32 v[52:53], v[52:53], v[242:243]
	v_pk_mul_f32 v[54:55], v[54:55], v[244:245]
	v_pk_mul_f32 v[48:49], v[48:49], v[246:247]
	v_pk_mul_f32 v[50:51], v[50:51], v[248:249]
	v_pk_fma_f32 v[52:53], v[52:53], 0.5, v[194:195] op_sel_hi:[1,0,1]
	v_pk_fma_f32 v[54:55], v[54:55], 0.5, v[196:197] op_sel_hi:[1,0,1]
	v_pk_fma_f32 v[48:49], v[48:49], 0.5, v[198:199] op_sel_hi:[1,0,1]
	v_pk_fma_f32 v[50:51], v[50:51], 0.5, v[200:201] op_sel_hi:[1,0,1]
	global_store_dwordx4 v139, v[52:55], s[42:43] offset:512
	global_store_dwordx4 v139, v[48:51], s[42:43] offset:528
	s_add_u32 s42, s42, 0x10000
	s_addc_u32 s43, s43, 0
	s_waitcnt vmcnt(22)
	v_pk_mul_f32 v[44:45], v[44:45], v[242:243]
	v_pk_mul_f32 v[46:47], v[46:47], v[244:245]
	v_pk_mul_f32 v[40:41], v[40:41], v[246:247]
	v_pk_mul_f32 v[42:43], v[42:43], v[248:249]
	v_pk_fma_f32 v[44:45], v[44:45], 0.5, v[202:203] op_sel_hi:[1,0,1]
	v_pk_fma_f32 v[46:47], v[46:47], 0.5, v[204:205] op_sel_hi:[1,0,1]
	v_pk_fma_f32 v[40:41], v[40:41], 0.5, v[206:207] op_sel_hi:[1,0,1]
	v_pk_fma_f32 v[42:43], v[42:43], 0.5, v[208:209] op_sel_hi:[1,0,1]
	global_store_dwordx4 v139, v[44:47], s[42:43] offset:512
	global_store_dwordx4 v139, v[40:43], s[42:43] offset:528
	s_add_u32 s42, s42, 0x10000
	s_addc_u32 s43, s43, 0
	s_waitcnt vmcnt(20)
	v_pk_mul_f32 v[36:37], v[36:37], v[242:243]
	v_pk_mul_f32 v[38:39], v[38:39], v[244:245]
	v_pk_mul_f32 v[32:33], v[32:33], v[246:247]
	v_pk_mul_f32 v[34:35], v[34:35], v[248:249]
	v_pk_fma_f32 v[36:37], v[36:37], 0.5, v[210:211] op_sel_hi:[1,0,1]
	v_pk_fma_f32 v[38:39], v[38:39], 0.5, v[212:213] op_sel_hi:[1,0,1]
	v_pk_fma_f32 v[32:33], v[32:33], 0.5, v[214:215] op_sel_hi:[1,0,1]
	v_pk_fma_f32 v[34:35], v[34:35], 0.5, v[216:217] op_sel_hi:[1,0,1]
	global_store_dwordx4 v139, v[36:39], s[42:43] offset:512
	global_store_dwordx4 v139, v[32:35], s[42:43] offset:528
	s_add_u32 s42, s42, 0x50000
	s_addc_u32 s43, s43, 0
	s_waitcnt vmcnt(18)
	v_pk_mul_f32 v[28:29], v[28:29], v[242:243]
	v_pk_mul_f32 v[30:31], v[30:31], v[244:245]
	v_pk_mul_f32 v[24:25], v[24:25], v[246:247]
	v_pk_mul_f32 v[26:27], v[26:27], v[248:249]
	v_pk_fma_f32 v[28:29], v[28:29], 0.5, v[218:219] op_sel_hi:[1,0,1]
	v_pk_fma_f32 v[30:31], v[30:31], 0.5, v[220:221] op_sel_hi:[1,0,1]
	v_pk_fma_f32 v[24:25], v[24:25], 0.5, v[222:223] op_sel_hi:[1,0,1]
	v_pk_fma_f32 v[26:27], v[26:27], 0.5, v[224:225] op_sel_hi:[1,0,1]
	global_store_dwordx4 v139, v[28:31], s[42:43] offset:512
	global_store_dwordx4 v139, v[24:27], s[42:43] offset:528
	s_add_u32 s42, s42, 0x10000
	s_addc_u32 s43, s43, 0
	s_waitcnt vmcnt(16)
	v_pk_mul_f32 v[20:21], v[20:21], v[242:243]
	v_pk_mul_f32 v[22:23], v[22:23], v[244:245]
	v_pk_mul_f32 v[16:17], v[16:17], v[246:247]
	v_pk_mul_f32 v[18:19], v[18:19], v[248:249]
	v_pk_fma_f32 v[20:21], v[20:21], 0.5, v[226:227] op_sel_hi:[1,0,1]
	v_pk_fma_f32 v[22:23], v[22:23], 0.5, v[228:229] op_sel_hi:[1,0,1]
	v_pk_fma_f32 v[16:17], v[16:17], 0.5, v[230:231] op_sel_hi:[1,0,1]
	v_pk_fma_f32 v[18:19], v[18:19], 0.5, v[232:233] op_sel_hi:[1,0,1]
	global_store_dwordx4 v139, v[20:23], s[42:43] offset:512
	global_store_dwordx4 v139, v[16:19], s[42:43] offset:528
	s_add_u32 s42, s42, 0x10000
	s_addc_u32 s43, s43, 0
	s_waitcnt vmcnt(14)
	v_pk_mul_f32 v[12:13], v[12:13], v[242:243]
	v_pk_mul_f32 v[14:15], v[14:15], v[244:245]
	v_pk_mul_f32 v[8:9], v[8:9], v[246:247]
	v_pk_mul_f32 v[10:11], v[10:11], v[248:249]
	v_pk_fma_f32 v[12:13], v[12:13], 0.5, v[178:179] op_sel_hi:[1,0,1]
	v_pk_fma_f32 v[14:15], v[14:15], 0.5, v[180:181] op_sel_hi:[1,0,1]
	v_pk_fma_f32 v[8:9], v[8:9], 0.5, v[182:183] op_sel_hi:[1,0,1]
	v_pk_fma_f32 v[10:11], v[10:11], 0.5, v[184:185] op_sel_hi:[1,0,1]
	global_store_dwordx4 v139, v[12:15], s[42:43] offset:512
	global_store_dwordx4 v139, v[8:11], s[42:43] offset:528
	s_add_u32 s42, s42, 0x10000
	s_addc_u32 s43, s43, 0
	s_waitcnt vmcnt(12)
	v_pk_mul_f32 v[4:5], v[4:5], v[242:243]
	v_pk_mul_f32 v[6:7], v[6:7], v[244:245]
	v_pk_mul_f32 v[0:1], v[0:1], v[246:247]
	v_pk_mul_f32 v[2:3], v[2:3], v[248:249]
	v_pk_fma_f32 v[4:5], v[4:5], 0.5, v[186:187] op_sel_hi:[1,0,1]
	v_pk_fma_f32 v[6:7], v[6:7], 0.5, v[188:189] op_sel_hi:[1,0,1]
	v_pk_fma_f32 v[0:1], v[0:1], 0.5, v[190:191] op_sel_hi:[1,0,1]
	v_pk_fma_f32 v[2:3], v[2:3], 0.5, v[192:193] op_sel_hi:[1,0,1]
	global_store_dwordx4 v139, v[4:7], s[42:43] offset:512
	global_store_dwordx4 v139, v[0:3], s[42:43] offset:528
	v_pk_mul_f32 v[200:201], v[132:133], v[132:133]
	v_pk_mul_f32 v[202:203], v[124:125], v[124:125]
	v_pk_mul_f32 v[204:205], v[116:117], v[116:117]
	v_pk_mul_f32 v[206:207], v[108:109], v[108:109]
	v_pk_mul_f32 v[208:209], v[100:101], v[100:101]
	v_pk_mul_f32 v[210:211], v[92:93], v[92:93]
	v_pk_mul_f32 v[212:213], v[76:77], v[76:77]
	v_pk_mul_f32 v[214:215], v[68:69], v[68:69]
	v_pk_fma_f32 v[200:201], v[134:135], v[134:135], v[200:201]
	v_pk_fma_f32 v[202:203], v[126:127], v[126:127], v[202:203]
	v_pk_fma_f32 v[204:205], v[118:119], v[118:119], v[204:205]
	v_pk_fma_f32 v[206:207], v[110:111], v[110:111], v[206:207]
	v_pk_fma_f32 v[208:209], v[102:103], v[102:103], v[208:209]
	v_pk_fma_f32 v[210:211], v[94:95], v[94:95], v[210:211]
	v_pk_fma_f32 v[212:213], v[78:79], v[78:79], v[212:213]
	v_pk_fma_f32 v[214:215], v[70:71], v[70:71], v[214:215]
	v_pk_fma_f32 v[200:201], v[128:129], v[128:129], v[200:201]
	v_pk_fma_f32 v[202:203], v[120:121], v[120:121], v[202:203]
	v_pk_fma_f32 v[204:205], v[112:113], v[112:113], v[204:205]
	v_pk_fma_f32 v[206:207], v[104:105], v[104:105], v[206:207]
	v_pk_fma_f32 v[208:209], v[96:97], v[96:97], v[208:209]
	v_pk_fma_f32 v[210:211], v[88:89], v[88:89], v[210:211]
	v_pk_fma_f32 v[212:213], v[72:73], v[72:73], v[212:213]
	v_pk_fma_f32 v[214:215], v[64:65], v[64:65], v[214:215]
	v_pk_fma_f32 v[200:201], v[130:131], v[130:131], v[200:201]
	v_pk_fma_f32 v[202:203], v[122:123], v[122:123], v[202:203]
	v_pk_fma_f32 v[204:205], v[114:115], v[114:115], v[204:205]
	v_pk_fma_f32 v[206:207], v[106:107], v[106:107], v[206:207]
	v_pk_fma_f32 v[208:209], v[98:99], v[98:99], v[208:209]
	v_pk_fma_f32 v[210:211], v[90:91], v[90:91], v[210:211]
	v_pk_fma_f32 v[212:213], v[74:75], v[74:75], v[212:213]
	v_pk_fma_f32 v[214:215], v[66:67], v[66:67], v[214:215]
	v_pk_fma_f32 v[200:201], v[60:61], v[60:61], v[200:201]
	v_pk_fma_f32 v[202:203], v[52:53], v[52:53], v[202:203]
	v_pk_fma_f32 v[204:205], v[44:45], v[44:45], v[204:205]
	v_pk_fma_f32 v[206:207], v[36:37], v[36:37], v[206:207]
	v_pk_fma_f32 v[208:209], v[28:29], v[28:29], v[208:209]
	v_pk_fma_f32 v[210:211], v[20:21], v[20:21], v[210:211]
	v_pk_fma_f32 v[212:213], v[12:13], v[12:13], v[212:213]
	v_pk_fma_f32 v[214:215], v[4:5], v[4:5], v[214:215]
	v_pk_fma_f32 v[200:201], v[62:63], v[62:63], v[200:201]
	v_pk_fma_f32 v[202:203], v[54:55], v[54:55], v[202:203]
	v_pk_fma_f32 v[204:205], v[46:47], v[46:47], v[204:205]
	v_pk_fma_f32 v[206:207], v[38:39], v[38:39], v[206:207]
	v_pk_fma_f32 v[208:209], v[30:31], v[30:31], v[208:209]
	v_pk_fma_f32 v[210:211], v[22:23], v[22:23], v[210:211]
	v_pk_fma_f32 v[212:213], v[14:15], v[14:15], v[212:213]
	v_pk_fma_f32 v[214:215], v[6:7], v[6:7], v[214:215]
	v_pk_fma_f32 v[200:201], v[56:57], v[56:57], v[200:201]
	v_pk_fma_f32 v[202:203], v[48:49], v[48:49], v[202:203]
	v_pk_fma_f32 v[204:205], v[40:41], v[40:41], v[204:205]
	v_pk_fma_f32 v[206:207], v[32:33], v[32:33], v[206:207]
	v_pk_fma_f32 v[208:209], v[24:25], v[24:25], v[208:209]
	v_pk_fma_f32 v[210:211], v[16:17], v[16:17], v[210:211]
	v_pk_fma_f32 v[212:213], v[8:9], v[8:9], v[212:213]
	v_pk_fma_f32 v[214:215], v[0:1], v[0:1], v[214:215]
	v_pk_fma_f32 v[200:201], v[58:59], v[58:59], v[200:201]
	v_pk_fma_f32 v[202:203], v[50:51], v[50:51], v[202:203]
	v_pk_fma_f32 v[204:205], v[42:43], v[42:43], v[204:205]
	v_pk_fma_f32 v[206:207], v[34:35], v[34:35], v[206:207]
	v_pk_fma_f32 v[208:209], v[26:27], v[26:27], v[208:209]
	v_pk_fma_f32 v[210:211], v[18:19], v[18:19], v[210:211]
	v_pk_fma_f32 v[212:213], v[10:11], v[10:11], v[212:213]
	v_pk_fma_f32 v[214:215], v[2:3], v[2:3], v[214:215]
	v_add_f32_e32 v216, v200, v201
	v_add_f32_e32 v217, v202, v203
	v_add_f32_e32 v218, v204, v205
	v_add_f32_e32 v219, v206, v207
	v_add_f32_e32 v220, v208, v209
	v_add_f32_e32 v221, v210, v211
	v_add_f32_e32 v222, v212, v213
	v_add_f32_e32 v223, v214, v215
	v_and_b32_e32 v224, 63, v154
	v_xor_b32_e32 v225, 32, v224
	v_xor_b32_e32 v224, 16, v224
	v_lshlrev_b32_e32 v224, 2, v224
	v_lshlrev_b32_e32 v225, 2, v225
	ds_bpermute_b32 v226, v224, v216
	ds_bpermute_b32 v227, v224, v217
	ds_bpermute_b32 v228, v224, v218
	ds_bpermute_b32 v229, v224, v219
	ds_bpermute_b32 v230, v224, v220
	ds_bpermute_b32 v231, v224, v221
	ds_bpermute_b32 v232, v224, v222
	ds_bpermute_b32 v233, v224, v223
	s_waitcnt lgkmcnt(0)
	v_add_f32_e32 v216, v216, v226
	v_add_f32_e32 v217, v217, v227
	v_add_f32_e32 v218, v218, v228
	v_add_f32_e32 v219, v219, v229
	v_add_f32_e32 v220, v220, v230
	v_add_f32_e32 v221, v221, v231
	v_add_f32_e32 v222, v222, v232
	v_add_f32_e32 v223, v223, v233
	ds_bpermute_b32 v226, v225, v216
	ds_bpermute_b32 v227, v225, v217
	ds_bpermute_b32 v228, v225, v218
	ds_bpermute_b32 v229, v225, v219
	ds_bpermute_b32 v230, v225, v220
	ds_bpermute_b32 v231, v225, v221
	ds_bpermute_b32 v232, v225, v222
	ds_bpermute_b32 v233, v225, v223
	s_waitcnt lgkmcnt(0)
	v_add_f32_e32 v216, v216, v226
	v_add_f32_e32 v217, v217, v227
	v_add_f32_e32 v218, v218, v228
	v_add_f32_e32 v219, v219, v229
	v_add_f32_e32 v220, v220, v230
	v_add_f32_e32 v221, v221, v231
	v_add_f32_e32 v222, v222, v232
	v_add_f32_e32 v223, v223, v233
	v_bfe_u32 v234, v154, 6, 2
	v_lshlrev_b32_e32 v234, 8, v234
	v_lshrrev_b32_e32 v235, 8, v154
	v_lshl_add_u32 v234, v235, 6, v234
	v_and_b32_e32 v235, 15, v154
	v_add_u32_e32 v234, v234, v235
	v_lshlrev_b32_e32 v234, 2, v234
	ds_write_b32 v234, v216 offset:0
	ds_write_b32 v234, v217 offset:64
	ds_write_b32 v234, v218 offset:128
	ds_write_b32 v234, v219 offset:192
	ds_write_b32 v234, v220 offset:512
	ds_write_b32 v234, v221 offset:576
	ds_write_b32 v234, v222 offset:640
	ds_write_b32 v234, v223 offset:704
	s_waitcnt lgkmcnt(0)
	s_barrier
	v_cmp_gt_u32_e32 vcc, 0x100, v154
	s_and_saveexec_b64 s[48:49], vcc
	v_lshlrev_b32_e32 v235, 2, v154
	ds_read_b32 v236, v235
	ds_read_b32 v237, v235 offset:1024
	ds_read_b32 v238, v235 offset:2048
	ds_read_b32 v239, v235 offset:3072
	s_lshl_b32 s50, s4, 3
	s_and_b32 s50, s50, 56
	s_bfe_u32 s51, s4, 0x30003
	s_or_b32 s50, s50, s51
	s_lshl_b32 s50, s50, 2
	s_lshr_b32 s51, s4, 6
	s_or_b32 s50, s50, s51
	s_lshl_b32 s50, s50, 10
	s_add_u32 s50, s50, s72
	s_addc_u32 s51, s73, 0
	s_add_u32 s50, s50, 0x8d00000
	s_addc_u32 s51, s51, 0
	s_waitcnt lgkmcnt(0)
	v_add_f32_e32 v236, v236, v237
	v_add_f32_e32 v238, v238, v239
	v_add_f32_e32 v236, v236, v238
	global_store_dword v235, v236, s[50:51]
	s_mov_b64 exec, s[48:49]
	s_mov_b32 s92, s4
	v_mov_b64_e32 v[242:243], v[0:1]
	v_mov_b64_e32 v[244:245], v[2:3]
	v_mov_b64_e32 v[246:247], v[4:5]
	v_mov_b64_e32 v[248:249], v[6:7]
	s_add_i32 s4, s4, s74
	s_add_i32 s9, s9, s20
	s_cmpk_lt_i32 s4, 0x100
	s_cbranch_scc0 .LBB0_705
